# v49_a1_k_loads_issued_early_in_bcum
# speedup vs baseline: 1.0414x; 1.0012x over previous
; #define LAS __attribute__((address_space(3)))
; __device__ __forceinline__ float bf2f(bf16_t v) { return __uint_as_float((unsigned)v << 16); }
; __device__ __forceinline__ void gla_bcum(KArgs a, int tid, int t0, int h, LAS float* segtot, LAS float* glrs, float (&bc)[32], float& tot) {
;     ...
;     for (int j = 0; j < 16; ++j) w2r[j] = a->gate_w2[j * 512 + col];
;     const float bias = a->gate_b[col];
;     *(LAS f32x4*)(glrs + tid * 4) = *(const f32x4*)(glr + (size_t)t0 * 16 + tid * 4);
;     __syncthreads();
;     float run = 0.f;
; #pragma unroll
;     for (int r = 0; r < 32; ++r) { const LAS f32x4* gp = (const LAS f32x4*)(glrs + (seg * 32 + r) * 16);
;         float z = bias;
; #pragma unroll
;         for (int q = 0; q < 4; ++q) { const f32x4 g = gp[q]; z += g[0] * w2r[4 * q] + g[1] * w2r[4 * q + 1] + g[2] * w2r[4 * q + 2] + g[3] * w2r[4 * q + 3]; }
;         const float la = (fminf(z, 0.f) - __logf(1.0f + __expf(-fabsf(z)))) * (1.0f / 16.0f);
;         run += la; bc[r] = run; }
; __device__ __forceinline__ void gla_a1(const Ctx& X, KArgs a, float* kvt, float* decb) {
;     ...
;               for (int e = 0; e < 8; ++e) { const int r = r8 * 8 + e; kd[e] = bf2f(proj[(size_t)(t0 + seg * 32 + r) * NMAIN + C_GK + h * 128 + d]) * __expf(tot - bc[r]); }
.LBB0_341:
	s_bfe_u32 s5, s10, 0x20005
	v_lshlrev_b32_e32 v2, 2, v8
	v_lshl_or_b32 v2, s5, 9, v2
	v_lshl_add_u64 v[20:21], s[12:13], 0, v[2:3]
	s_and_b32 s0, s2, 0xfffff000
	s_and_b32 s1, s3, 0xf80
	v_add_co_u32_e64 v28, s[6:7], s29, v20
	s_or_b32 s20, s0, s1
	s_nop 0
	v_addc_co_u32_e64 v29, s[6:7], 0, v21, s[6:7]
	s_movk_i32 s0, 0x2000
	v_add_co_u32_e64 v14, s[6:7], s0, v20
	s_movk_i32 s0, 0x3000
	s_nop 0
	v_addc_co_u32_e64 v15, s[6:7], 0, v21, s[6:7]
	s_ashr_i32 s21, s20, 31
	v_add_co_u32_e64 v42, s[6:7], s0, v20
	s_lshl_b64 s[0:1], s[20:21], 6
	s_nop 0
	v_addc_co_u32_e64 v43, s[6:7], 0, v21, s[6:7]
	v_lshl_add_u64 v[16:17], v[10:11], 0, s[0:1]
	s_movk_i32 s0, 0x4000
	s_barrier
	global_load_dwordx4 v[44:47], v[16:17], off
	v_add_co_u32_e64 v16, s[6:7], s0, v20
	s_movk_i32 s0, 0x5000
	s_nop 0
	v_addc_co_u32_e64 v17, s[6:7], 0, v21, s[6:7]
	v_add_co_u32_e64 v48, s[6:7], s0, v20
	s_movk_i32 s0, 0x6000
	s_nop 0
	v_addc_co_u32_e64 v49, s[6:7], 0, v21, s[6:7]
	v_add_co_u32_e64 v50, s[6:7], s0, v20
	s_movk_i32 s0, 0x7000
	s_nop 0
	v_addc_co_u32_e64 v51, s[6:7], 0, v21, s[6:7]
	global_load_dword v24, v2, s[12:13]
	global_load_dword v26, v2, s[12:13] offset:2048
	global_load_dword v22, v[14:15], off offset:-4096
	global_load_dword v25, v[14:15], off
	global_load_dword v27, v[14:15], off offset:2048
	global_load_dword v23, v[16:17], off offset:-4096
	s_nop 0
	global_load_dword v14, v[16:17], off
	global_load_dword v18, v[16:17], off offset:2048
	s_nop 0
	global_load_dword v16, v[50:51], off offset:-4096
	global_load_dword v15, v[50:51], off
	global_load_dword v19, v[50:51], off offset:2048
	v_add_co_u32_e64 v20, s[6:7], s0, v20
	v_readfirstlane_b32 s1, v32
	s_nop 0
	v_addc_co_u32_e64 v21, s[6:7], 0, v21, s[6:7]
	global_load_dword v28, v[28:29], off offset:2048
	s_nop 0
	global_load_dword v29, v[42:43], off offset:2048
	global_load_dword v17, v[20:21], off
	s_nop 0
	global_load_dword v21, v[20:21], off offset:2048
	s_nop 0
	global_load_dword v20, v[48:49], off offset:2048
	s_nop 0
	global_load_dword v2, v2, s[14:15]
	s_ashr_i32 s0, s1, 7
	s_lshl_b32 s6, s0, 11
	s_add_i32 s6, s6, 0
	v_mov_b32_e32 v42, s6
	s_and_b32 s1, s1, 0x3fffff80
	s_cmp_gt_i32 s0, 0
	s_waitcnt vmcnt(17)
	ds_write_b128 v33, v[44:47] offset:34816
	s_waitcnt lgkmcnt(0)
	s_barrier
	ds_read_b128 v[44:47], v42 offset:34816
	ds_read_b128 v[48:51], v42 offset:34832
	ds_read_b128 v[52:55], v42 offset:34848
	ds_read_b128 v[56:59], v42 offset:34864
	ds_read_b128 v[60:63], v42 offset:34880
	ds_read_b128 v[64:67], v42 offset:34896
	s_waitcnt lgkmcnt(4)
	v_mov_b32_e32 v69, v48
	v_mov_b32_e32 v48, v45
	v_mov_b32_e32 v68, v44
	v_mov_b32_e32 v44, v46
	v_mov_b32_e32 v45, v50
	v_mov_b32_e32 v50, v47
	s_waitcnt lgkmcnt(2)
	v_mov_b32_e32 v47, v56
	v_mov_b32_e32 v56, v53
	v_mov_b32_e32 v46, v52
	s_waitcnt vmcnt(12)
	v_pk_mul_f32 v[48:49], v[26:27], v[48:49]
	v_mov_b32_e32 v52, v54
	v_pk_fma_f32 v[48:49], v[24:25], v[68:69], v[48:49]
	v_mov_b32_e32 v53, v58
	v_mov_b32_e32 v58, v55
	s_waitcnt vmcnt(6)
	v_pk_mul_f32 v[54:55], v[18:19], v[56:57]
	v_pk_fma_f32 v[44:45], v[22:23], v[44:45], v[48:49]
	v_pk_fma_f32 v[46:47], v[14:15], v[46:47], v[54:55]
	s_waitcnt vmcnt(4)
	v_pk_fma_f32 v[44:45], v[28:29], v[50:51], v[44:45]
	s_waitcnt vmcnt(3)
	v_pk_fma_f32 v[46:47], v[16:17], v[52:53], v[46:47]
	s_waitcnt vmcnt(0)
	v_add_u32_e32 v178, s20, v35
	v_mov_b64_e32 v[176:177], s[18:19]
	v_mad_i64_i32 v[176:177], s[100:101], v178, s35, v[176:177]
	s_mul_i32 s98, s5, 0x100
	s_mov_b32 s99, 0
	v_lshl_add_u64 v[176:177], v[176:177], 0, s[98:99]
	v_lshlrev_b32_e32 v178, 1, v8
	v_mov_b32_e32 v179, 0
	v_lshl_add_u64 v[176:177], v[176:177], 0, v[178:179]
	s_movk_i32 s98, 0x2a00
	global_load_ushort v192, v[176:177], off offset:1024
	v_lshl_add_u64 v[176:177], v[176:177], 0, s[98:99]
	global_load_ushort v193, v[176:177], off offset:1024
	v_lshl_add_u64 v[176:177], v[176:177], 0, s[98:99]
	global_load_ushort v194, v[176:177], off offset:1024
	v_lshl_add_u64 v[176:177], v[176:177], 0, s[98:99]
	global_load_ushort v195, v[176:177], off offset:1024
	v_lshl_add_u64 v[176:177], v[176:177], 0, s[98:99]
	global_load_ushort v196, v[176:177], off offset:1024
	v_lshl_add_u64 v[176:177], v[176:177], 0, s[98:99]
	global_load_ushort v197, v[176:177], off offset:1024
	v_lshl_add_u64 v[176:177], v[176:177], 0, s[98:99]
	global_load_ushort v198, v[176:177], off offset:1024
	v_lshl_add_u64 v[176:177], v[176:177], 0, s[98:99]
	global_load_ushort v199, v[176:177], off offset:1024
	v_lshl_add_u64 v[176:177], v[176:177], 0, s[98:99]
	global_load_ushort v200, v[176:177], off offset:1024
	v_lshl_add_u64 v[176:177], v[176:177], 0, s[98:99]
	global_load_ushort v201, v[176:177], off offset:1024
	v_lshl_add_u64 v[176:177], v[176:177], 0, s[98:99]
	global_load_ushort v202, v[176:177], off offset:1024
	v_lshl_add_u64 v[176:177], v[176:177], 0, s[98:99]
	global_load_ushort v203, v[176:177], off offset:1024
	v_lshl_add_u64 v[176:177], v[176:177], 0, s[98:99]
	global_load_ushort v204, v[176:177], off offset:1024
	v_lshl_add_u64 v[176:177], v[176:177], 0, s[98:99]
	global_load_ushort v205, v[176:177], off offset:1024
	v_lshl_add_u64 v[176:177], v[176:177], 0, s[98:99]
	global_load_ushort v206, v[176:177], off offset:1024
	v_lshl_add_u64 v[176:177], v[176:177], 0, s[98:99]
	global_load_ushort v207, v[176:177], off offset:1024
	v_lshl_add_u64 v[176:177], v[176:177], 0, s[98:99]
	global_load_ushort v208, v[176:177], off offset:1024
	v_lshl_add_u64 v[176:177], v[176:177], 0, s[98:99]
	global_load_ushort v209, v[176:177], off offset:1024
	v_lshl_add_u64 v[176:177], v[176:177], 0, s[98:99]
	global_load_ushort v210, v[176:177], off offset:1024
; #define LAS __attribute__((address_space(3)))
; __device__ __forceinline__ float bf2f(bf16_t v) { return __uint_as_float((unsigned)v << 16); }
; __device__ __forceinline__ void gla_bcum(KArgs a, int tid, int t0, int h, LAS float* segtot, LAS float* glrs, float (&bc)[32], float& tot) {
;     ...
;     for (int r = 0; r < 32; ++r) { const LAS f32x4* gp = (const LAS f32x4*)(glrs + (seg * 32 + r) * 16);
;         float z = bias;
; #pragma unroll
;         for (int q = 0; q < 4; ++q) { const f32x4 g = gp[q]; z += g[0] * w2r[4 * q] + g[1] * w2r[4 * q + 1] + g[2] * w2r[4 * q + 2] + g[3] * w2r[4 * q + 3]; }
;         const float la = (fminf(z, 0.f) - __logf(1.0f + __expf(-fabsf(z)))) * (1.0f / 16.0f);
;         run += la; bc[r] = run; }
; __device__ __forceinline__ void gla_a1(const Ctx& X, KArgs a, float* kvt, float* decb) {
;     ...
;               for (int e = 0; e < 8; ++e) { const int r = r8 * 8 + e; kd[e] = bf2f(proj[(size_t)(t0 + seg * 32 + r) * NMAIN + C_GK + h * 128 + d]) * __expf(tot - bc[r]); }
	v_lshl_add_u64 v[176:177], v[176:177], 0, s[98:99]
	global_load_ushort v211, v[176:177], off offset:1024
	v_lshl_add_u64 v[176:177], v[176:177], 0, s[98:99]
	global_load_ushort v212, v[176:177], off offset:1024
	v_lshl_add_u64 v[176:177], v[176:177], 0, s[98:99]
	global_load_ushort v213, v[176:177], off offset:1024
	v_lshl_add_u64 v[176:177], v[176:177], 0, s[98:99]
	global_load_ushort v214, v[176:177], off offset:1024
	v_lshl_add_u64 v[176:177], v[176:177], 0, s[98:99]
	global_load_ushort v215, v[176:177], off offset:1024
	v_lshl_add_u64 v[176:177], v[176:177], 0, s[98:99]
	global_load_ushort v216, v[176:177], off offset:1024
	v_lshl_add_u64 v[176:177], v[176:177], 0, s[98:99]
	global_load_ushort v217, v[176:177], off offset:1024
	v_lshl_add_u64 v[176:177], v[176:177], 0, s[98:99]
	global_load_ushort v218, v[176:177], off offset:1024
	v_lshl_add_u64 v[176:177], v[176:177], 0, s[98:99]
	global_load_ushort v219, v[176:177], off offset:1024
	v_lshl_add_u64 v[176:177], v[176:177], 0, s[98:99]
	global_load_ushort v220, v[176:177], off offset:1024
	v_lshl_add_u64 v[176:177], v[176:177], 0, s[98:99]
	global_load_ushort v221, v[176:177], off offset:1024
	v_lshl_add_u64 v[176:177], v[176:177], 0, s[98:99]
	global_load_ushort v222, v[176:177], off offset:1024
	v_lshl_add_u64 v[176:177], v[176:177], 0, s[98:99]
	global_load_ushort v223, v[176:177], off offset:1024
	v_add_f32_e32 v13, v2, v44
	v_pk_fma_f32 v[46:47], v[20:21], v[58:59], v[46:47]
	v_add_f32_e32 v13, v13, v45
	v_add_f32_e32 v13, v13, v46
	v_add_f32_e32 v13, v13, v47
	v_mul_f32_e64 v43, |v13|, s4
	v_exp_f32_e32 v43, v43
	s_waitcnt lgkmcnt(0)
	v_mov_b32_e32 v45, v64
	v_mov_b32_e32 v64, v61
	v_mov_b32_e32 v44, v60
	v_add_f32_e32 v43, 1.0, v43
	v_min_f32_e32 v13, 0, v13
	s_nop 0
	v_log_f32_e32 v43, v43
	v_pk_mul_f32 v[46:47], v[26:27], v[64:65]
	v_pk_fma_f32 v[44:45], v[24:25], v[44:45], v[46:47]
	v_mul_f32_e32 v46, 0x3f317217, v43
	v_fma_f32 v54, v43, s36, -v46
	v_mov_b32_e32 v46, v62
	v_mov_b32_e32 v47, v66
	v_pk_fma_f32 v[52:53], v[22:23], v[46:47], v[44:45]
	ds_read_b128 v[44:47], v42 offset:34912
	ds_read_b128 v[48:51], v42 offset:34928
	v_mov_b32_e32 v66, v63
	v_pk_fma_f32 v[52:53], v[28:29], v[66:67], v[52:53]
	v_fmac_f32_e32 v54, 0x3377d1cf, v43
	v_add_f32_e32 v52, v2, v52
	v_add_f32_e32 v55, v52, v53
	s_waitcnt lgkmcnt(0)
	v_mov_b32_e32 v53, v48
	v_mov_b32_e32 v48, v45
	v_mov_b32_e32 v52, v44
	v_pk_mul_f32 v[44:45], v[18:19], v[48:49]
	v_mov_b32_e32 v48, v46
	v_pk_fma_f32 v[44:45], v[14:15], v[52:53], v[44:45]
	v_mov_b32_e32 v49, v50
	v_pk_fma_f32 v[44:45], v[16:17], v[48:49], v[44:45]
	v_mov_b32_e32 v50, v47
	v_pk_fma_f32 v[44:45], v[20:21], v[50:51], v[44:45]
	v_fmac_f32_e32 v54, 0x3f317217, v43
	v_add_f32_e32 v44, v55, v44
	v_add_f32_e32 v45, v44, v45
	v_mul_f32_e64 v44, |v45|, s4
	v_exp_f32_e32 v44, v44
	v_mov_b32_e32 v43, v54
	v_add_f32_e32 v44, 1.0, v44
	v_sub_f32_e32 v13, v13, v43
	s_mov_b32 s8, 0x3d800000
	ds_read_b128 v[46:49], v42 offset:34944
	ds_read_b128 v[50:53], v42 offset:34960
	v_log_f32_e32 v58, v44
	v_fma_f32 v44, v13, s8, 0
	v_min_f32_e32 v13, 0, v45
	s_waitcnt lgkmcnt(1)
	v_mov_b32_e32 v54, v46
	s_waitcnt lgkmcnt(0)
	v_mov_b32_e32 v55, v50
	v_mov_b32_e32 v50, v47
	v_pk_mul_f32 v[46:47], v[26:27], v[50:51]
	v_mov_b32_e32 v50, v48
	v_pk_fma_f32 v[46:47], v[24:25], v[54:55], v[46:47]
	v_mov_b32_e32 v51, v52
	v_pk_fma_f32 v[50:51], v[22:23], v[50:51], v[46:47]
	v_mov_b32_e32 v52, v49
	ds_read_b128 v[46:49], v42 offset:34976
	ds_read_b128 v[54:57], v42 offset:34992
	v_pk_fma_f32 v[50:51], v[28:29], v[52:53], v[50:51]
	v_mul_f32_e32 v43, 0x3f317217, v58
	v_add_f32_e32 v45, v2, v50
	v_add_f32_e32 v45, v45, v51
	s_waitcnt lgkmcnt(0)
	v_mov_b32_e32 v51, v54
	v_mov_b32_e32 v54, v47
	v_mov_b32_e32 v50, v46
	v_pk_mul_f32 v[46:47], v[18:19], v[54:55]
	v_fma_f32 v43, v58, s36, -v43
	v_pk_fma_f32 v[46:47], v[14:15], v[50:51], v[46:47]
	v_mov_b32_e32 v50, v48
	v_mov_b32_e32 v51, v56
	v_pk_fma_f32 v[46:47], v[16:17], v[50:51], v[46:47]
	v_mov_b32_e32 v56, v49
	v_pk_fma_f32 v[46:47], v[20:21], v[56:57], v[46:47]
	ds_read_b128 v[48:51], v42 offset:35008
	ds_read_b128 v[52:55], v42 offset:35024
	v_add_f32_e32 v45, v45, v46
	v_add_f32_e32 v45, v45, v47
	v_mul_f32_e64 v46, |v45|, s4
	v_exp_f32_e32 v46, v46
	s_waitcnt lgkmcnt(0)
	v_mov_b32_e32 v57, v52
	v_mov_b32_e32 v52, v49
	v_fmac_f32_e32 v43, 0x3377d1cf, v58
	v_mov_b32_e32 v56, v48
	v_pk_mul_f32 v[48:49], v[26:27], v[52:53]
	v_fmac_f32_e32 v43, 0x3f317217, v58
	v_pk_fma_f32 v[48:49], v[24:25], v[56:57], v[48:49]
	v_mov_b32_e32 v52, v50
	v_mov_b32_e32 v53, v54
	v_mov_b32_e32 v43, v43
	v_add_f32_e32 v46, 1.0, v46
	v_pk_fma_f32 v[52:53], v[22:23], v[52:53], v[48:49]
	v_mov_b32_e32 v54, v51
	ds_read_b128 v[48:51], v42 offset:35040
	ds_read_b128 v[56:59], v42 offset:35056
	v_sub_f32_e32 v13, v13, v43
	v_pk_fma_f32 v[52:53], v[28:29], v[54:55], v[52:53]
	v_log_f32_e32 v47, v46
	v_fmamk_f32 v46, v13, 0x3d800000, v44
	v_min_f32_e32 v13, 0, v45
	v_add_f32_e32 v45, v2, v52
	v_add_f32_e32 v45, v45, v53
	s_waitcnt lgkmcnt(0)
	v_mov_b32_e32 v53, v56
	v_mov_b32_e32 v56, v49
	v_mov_b32_e32 v52, v48
	v_pk_mul_f32 v[48:49], v[18:19], v[56:57]
	v_mul_f32_e32 v43, 0x3f317217, v47
	v_pk_fma_f32 v[48:49], v[14:15], v[52:53], v[48:49]
	v_mov_b32_e32 v52, v50
	v_mov_b32_e32 v53, v58
	v_pk_fma_f32 v[48:49], v[16:17], v[52:53], v[48:49]
	v_mov_b32_e32 v58, v51
	v_pk_fma_f32 v[48:49], v[20:21], v[58:59], v[48:49]
	v_fma_f32 v43, v47, s36, -v43
	v_add_f32_e32 v45, v45, v48
	v_add_f32_e32 v45, v45, v49
	v_mul_f32_e64 v48, |v45|, s4
	v_exp_f32_e32 v48, v48
	v_fmac_f32_e32 v43, 0x3377d1cf, v47
	v_fmac_f32_e32 v43, 0x3f317217, v47
	s_nop 1
	v_mov_b32_e32 v43, v43
	v_add_f32_e32 v47, 1.0, v48
	v_sub_f32_e32 v13, v13, v43
	v_min_f32_e32 v43, 0, v45
	ds_read_b128 v[48:51], v42 offset:35072
	ds_read_b128 v[52:55], v42 offset:35088
	v_log_f32_e32 v47, v47
	v_fmamk_f32 v13, v13, 0x3d800000, v46
	s_waitcnt lgkmcnt(1)
; #define LAS __attribute__((address_space(3)))
; __device__ __forceinline__ void gla_bcum(KArgs a, int tid, int t0, int h, LAS float* segtot, LAS float* glrs, float (&bc)[32], float& tot) {
;     ...
;     for (int r = 0; r < 32; ++r) { const LAS f32x4* gp = (const LAS f32x4*)(glrs + (seg * 32 + r) * 16);
;         float z = bias;
; #pragma unroll
;         for (int q = 0; q < 4; ++q) { const f32x4 g = gp[q]; z += g[0] * w2r[4 * q] + g[1] * w2r[4 * q + 1] + g[2] * w2r[4 * q + 2] + g[3] * w2r[4 * q + 3]; }
;         const float la = (fminf(z, 0.f) - __logf(1.0f + __expf(-fabsf(z)))) * (1.0f / 16.0f);
;         run += la; bc[r] = run; }
	v_mov_b32_e32 v56, v48
	s_waitcnt lgkmcnt(0)
	v_mov_b32_e32 v57, v52
	v_mov_b32_e32 v52, v49
	v_pk_mul_f32 v[48:49], v[26:27], v[52:53]
	v_mov_b32_e32 v52, v50
	v_pk_fma_f32 v[48:49], v[24:25], v[56:57], v[48:49]
	v_mov_b32_e32 v53, v54
	v_pk_fma_f32 v[52:53], v[22:23], v[52:53], v[48:49]
	v_mov_b32_e32 v54, v51
	ds_read_b128 v[48:51], v42 offset:35104
	ds_read_b128 v[56:59], v42 offset:35120
	v_pk_fma_f32 v[52:53], v[28:29], v[54:55], v[52:53]
	v_mul_f32_e32 v45, 0x3f317217, v47
	v_add_f32_e32 v52, v2, v52
	v_add_f32_e32 v54, v52, v53
	s_waitcnt lgkmcnt(0)
	v_mov_b32_e32 v53, v56
	v_mov_b32_e32 v56, v49
	v_mov_b32_e32 v52, v48
	v_pk_mul_f32 v[48:49], v[18:19], v[56:57]
	v_fma_f32 v45, v47, s36, -v45
	v_pk_fma_f32 v[48:49], v[14:15], v[52:53], v[48:49]
	v_mov_b32_e32 v52, v50
	v_mov_b32_e32 v53, v58
	v_pk_fma_f32 v[48:49], v[16:17], v[52:53], v[48:49]
	v_mov_b32_e32 v58, v51
	v_pk_fma_f32 v[48:49], v[20:21], v[58:59], v[48:49]
	v_fmac_f32_e32 v45, 0x3377d1cf, v47
	v_add_f32_e32 v48, v54, v48
	v_add_f32_e32 v48, v48, v49
	v_mul_f32_e64 v49, |v48|, s4
	v_exp_f32_e32 v49, v49
	v_fmac_f32_e32 v45, 0x3f317217, v47
	s_nop 1
	v_mov_b32_e32 v45, v45
	v_add_f32_e32 v47, 1.0, v49
	v_sub_f32_e32 v43, v43, v45
	v_min_f32_e32 v45, 0, v48
	ds_read_b128 v[48:51], v42 offset:35136
	ds_read_b128 v[52:55], v42 offset:35152
	v_log_f32_e32 v47, v47
	v_fmamk_f32 v43, v43, 0x3d800000, v13
	v_mul_f32_e32 v56, 0x3f317217, v47
	s_waitcnt lgkmcnt(0)
	v_mov_b32_e32 v57, v52
	v_mov_b32_e32 v52, v49
	v_fma_f32 v60, v47, s36, -v56
	v_mov_b32_e32 v56, v48
	v_pk_mul_f32 v[48:49], v[26:27], v[52:53]
	v_mov_b32_e32 v52, v50
	v_pk_fma_f32 v[48:49], v[24:25], v[56:57], v[48:49]
	v_mov_b32_e32 v53, v54
	v_pk_fma_f32 v[52:53], v[22:23], v[52:53], v[48:49]
	v_mov_b32_e32 v54, v51
	ds_read_b128 v[48:51], v42 offset:35168
	ds_read_b128 v[56:59], v42 offset:35184
	v_pk_fma_f32 v[52:53], v[28:29], v[54:55], v[52:53]
	v_fmac_f32_e32 v60, 0x3377d1cf, v47
	v_add_f32_e32 v52, v2, v52
	v_add_f32_e32 v54, v52, v53
	s_waitcnt lgkmcnt(0)
	v_mov_b32_e32 v53, v56
	v_mov_b32_e32 v56, v49
	v_mov_b32_e32 v52, v48
	v_pk_mul_f32 v[48:49], v[18:19], v[56:57]
	v_fmac_f32_e32 v60, 0x3f317217, v47
	v_pk_fma_f32 v[48:49], v[14:15], v[52:53], v[48:49]
	v_mov_b32_e32 v52, v50
	v_mov_b32_e32 v53, v58
	v_pk_fma_f32 v[48:49], v[16:17], v[52:53], v[48:49]
	v_mov_b32_e32 v58, v51
	v_pk_fma_f32 v[48:49], v[20:21], v[58:59], v[48:49]
	v_add_f32_e32 v48, v54, v48
	v_add_f32_e32 v48, v48, v49
	v_mul_f32_e64 v49, |v48|, s4
	v_exp_f32_e32 v49, v49
	v_mov_b32_e32 v47, v60
	v_add_f32_e32 v49, 1.0, v49
	v_sub_f32_e32 v45, v45, v47
	v_min_f32_e32 v47, 0, v48
	v_log_f32_e32 v60, v49
	ds_read_b128 v[48:51], v42 offset:35200
	ds_read_b128 v[52:55], v42 offset:35216
	v_fmamk_f32 v45, v45, 0x3d800000, v43
	v_mul_f32_e32 v56, 0x3f317217, v60
	v_fma_f32 v61, v60, s36, -v56
	s_waitcnt lgkmcnt(0)
	v_mov_b32_e32 v57, v52
	v_mov_b32_e32 v52, v49
	v_mov_b32_e32 v56, v48
	v_pk_mul_f32 v[48:49], v[26:27], v[52:53]
	v_mov_b32_e32 v52, v50
	v_pk_fma_f32 v[48:49], v[24:25], v[56:57], v[48:49]
	v_mov_b32_e32 v53, v54
	v_pk_fma_f32 v[52:53], v[22:23], v[52:53], v[48:49]
	v_mov_b32_e32 v54, v51
	ds_read_b128 v[48:51], v42 offset:35232
	ds_read_b128 v[56:59], v42 offset:35248
	v_pk_fma_f32 v[52:53], v[28:29], v[54:55], v[52:53]
	v_fmac_f32_e32 v61, 0x3377d1cf, v60
	v_add_f32_e32 v52, v2, v52
	v_add_f32_e32 v54, v52, v53
	s_waitcnt lgkmcnt(0)
	v_mov_b32_e32 v53, v56
	v_mov_b32_e32 v56, v49
	v_mov_b32_e32 v52, v48
	v_pk_mul_f32 v[48:49], v[18:19], v[56:57]
	v_fmac_f32_e32 v61, 0x3f317217, v60
	v_pk_fma_f32 v[48:49], v[14:15], v[52:53], v[48:49]
	v_mov_b32_e32 v52, v50
	v_mov_b32_e32 v53, v58
	v_pk_fma_f32 v[48:49], v[16:17], v[52:53], v[48:49]
	v_mov_b32_e32 v58, v51
	v_pk_fma_f32 v[48:49], v[20:21], v[58:59], v[48:49]
	v_add_f32_e32 v48, v54, v48
	v_add_f32_e32 v48, v48, v49
	v_mul_f32_e64 v49, |v48|, s4
	v_exp_f32_e32 v49, v49
	v_mov_b32_e32 v50, v61
	v_add_f32_e32 v49, 1.0, v49
	v_sub_f32_e32 v47, v47, v50
	v_min_f32_e32 v61, 0, v48
	v_log_f32_e32 v60, v49
	ds_read_b128 v[48:51], v42 offset:35264
	ds_read_b128 v[52:55], v42 offset:35280
	v_fmamk_f32 v47, v47, 0x3d800000, v45
	v_mul_f32_e32 v56, 0x3f317217, v60
	v_fma_f32 v62, v60, s36, -v56
	s_waitcnt lgkmcnt(0)
	v_mov_b32_e32 v57, v52
	v_mov_b32_e32 v52, v49
	v_mov_b32_e32 v56, v48
	v_pk_mul_f32 v[48:49], v[26:27], v[52:53]
	v_mov_b32_e32 v52, v50
	v_pk_fma_f32 v[48:49], v[24:25], v[56:57], v[48:49]
	v_mov_b32_e32 v53, v54
	v_pk_fma_f32 v[52:53], v[22:23], v[52:53], v[48:49]
	v_mov_b32_e32 v54, v51
	ds_read_b128 v[48:51], v42 offset:35296
	ds_read_b128 v[56:59], v42 offset:35312
	v_pk_fma_f32 v[52:53], v[28:29], v[54:55], v[52:53]
	v_fmac_f32_e32 v62, 0x3377d1cf, v60
	v_add_f32_e32 v52, v2, v52
	v_add_f32_e32 v54, v52, v53
	s_waitcnt lgkmcnt(0)
	v_mov_b32_e32 v53, v56
	v_mov_b32_e32 v56, v49
	v_mov_b32_e32 v52, v48
	v_pk_mul_f32 v[48:49], v[18:19], v[56:57]
	v_fmac_f32_e32 v62, 0x3f317217, v60
	v_pk_fma_f32 v[48:49], v[14:15], v[52:53], v[48:49]
	v_mov_b32_e32 v52, v50
	v_mov_b32_e32 v53, v58
	v_pk_fma_f32 v[48:49], v[16:17], v[52:53], v[48:49]
	v_mov_b32_e32 v58, v51
	v_pk_fma_f32 v[48:49], v[20:21], v[58:59], v[48:49]
	v_add_f32_e32 v48, v54, v48
	v_add_f32_e32 v49, v48, v49
	v_mul_f32_e64 v48, |v49|, s4
	v_exp_f32_e32 v48, v48
	v_mov_b32_e32 v50, v62
	v_add_f32_e32 v48, 1.0, v48
	v_min_f32_e32 v49, 0, v49
	s_nop 0
	v_log_f32_e32 v62, v48
	v_sub_f32_e32 v48, v61, v50
	ds_read_b128 v[50:53], v42 offset:35328
	ds_read_b128 v[54:57], v42 offset:35344
	v_fmamk_f32 v48, v48, 0x3d800000, v47
	v_mul_f32_e32 v58, 0x3f317217, v62
	v_fma_f32 v63, v62, s36, -v58
	s_waitcnt lgkmcnt(1)
; #define LAS __attribute__((address_space(3)))
; __device__ __forceinline__ void gla_bcum(KArgs a, int tid, int t0, int h, LAS float* segtot, LAS float* glrs, float (&bc)[32], float& tot) {
;     ...
;     for (int r = 0; r < 32; ++r) { const LAS f32x4* gp = (const LAS f32x4*)(glrs + (seg * 32 + r) * 16);
;         float z = bias;
; #pragma unroll
;         for (int q = 0; q < 4; ++q) { const f32x4 g = gp[q]; z += g[0] * w2r[4 * q] + g[1] * w2r[4 * q + 1] + g[2] * w2r[4 * q + 2] + g[3] * w2r[4 * q + 3]; }
;         const float la = (fminf(z, 0.f) - __logf(1.0f + __expf(-fabsf(z)))) * (1.0f / 16.0f);
;         run += la; bc[r] = run; }
	v_mov_b32_e32 v58, v50
	s_waitcnt lgkmcnt(0)
	v_mov_b32_e32 v59, v54
	v_mov_b32_e32 v54, v51
	v_pk_mul_f32 v[50:51], v[26:27], v[54:55]
	v_mov_b32_e32 v54, v52
	v_pk_fma_f32 v[50:51], v[24:25], v[58:59], v[50:51]
	v_mov_b32_e32 v55, v56
	v_pk_fma_f32 v[54:55], v[22:23], v[54:55], v[50:51]
	v_mov_b32_e32 v56, v53
	ds_read_b128 v[50:53], v42 offset:35360
	ds_read_b128 v[58:61], v42 offset:35376
	v_pk_fma_f32 v[54:55], v[28:29], v[56:57], v[54:55]
	v_fmac_f32_e32 v63, 0x3377d1cf, v62
	v_add_f32_e32 v54, v2, v54
	v_add_f32_e32 v56, v54, v55
	s_waitcnt lgkmcnt(0)
	v_mov_b32_e32 v55, v58
	v_mov_b32_e32 v58, v51
	v_mov_b32_e32 v54, v50
	v_pk_mul_f32 v[50:51], v[18:19], v[58:59]
	v_fmac_f32_e32 v63, 0x3f317217, v62
	v_pk_fma_f32 v[50:51], v[14:15], v[54:55], v[50:51]
	v_mov_b32_e32 v54, v52
	v_mov_b32_e32 v55, v60
	v_pk_fma_f32 v[50:51], v[16:17], v[54:55], v[50:51]
	v_mov_b32_e32 v60, v53
	v_pk_fma_f32 v[50:51], v[20:21], v[60:61], v[50:51]
	v_add_f32_e32 v50, v56, v50
	v_add_f32_e32 v50, v50, v51
	v_mul_f32_e64 v51, |v50|, s4
	v_exp_f32_e32 v51, v51
	s_nop 0
	v_add_f32_e32 v51, 1.0, v51
	v_mov_b32_e32 v52, v63
	v_min_f32_e32 v63, 0, v50
	v_log_f32_e32 v62, v51
	v_mov_b32_e32 v51, v52
	v_sub_f32_e32 v49, v49, v51
	ds_read_b128 v[50:53], v42 offset:35392
	ds_read_b128 v[54:57], v42 offset:35408
	v_mul_f32_e32 v58, 0x3f317217, v62
	v_fma_f32 v64, v62, s36, -v58
	v_fmac_f32_e32 v64, 0x3377d1cf, v62
	s_waitcnt lgkmcnt(1)
	v_mov_b32_e32 v58, v50
	s_waitcnt lgkmcnt(0)
	v_mov_b32_e32 v59, v54
	v_mov_b32_e32 v54, v51
	v_pk_mul_f32 v[50:51], v[26:27], v[54:55]
	v_mov_b32_e32 v54, v52
	v_pk_fma_f32 v[50:51], v[24:25], v[58:59], v[50:51]
	v_mov_b32_e32 v55, v56
	v_pk_fma_f32 v[54:55], v[22:23], v[54:55], v[50:51]
	v_mov_b32_e32 v56, v53
	ds_read_b128 v[50:53], v42 offset:35424
	ds_read_b128 v[58:61], v42 offset:35440
	v_pk_fma_f32 v[54:55], v[28:29], v[56:57], v[54:55]
	v_fmac_f32_e32 v64, 0x3f317217, v62
	v_add_f32_e32 v54, v2, v54
	v_add_f32_e32 v56, v54, v55
	s_waitcnt lgkmcnt(0)
	v_mov_b32_e32 v55, v58
	v_mov_b32_e32 v58, v51
	v_mov_b32_e32 v54, v50
	v_pk_mul_f32 v[50:51], v[18:19], v[58:59]
	v_pk_fma_f32 v[50:51], v[14:15], v[54:55], v[50:51]
	v_mov_b32_e32 v54, v52
	v_mov_b32_e32 v55, v60
	v_pk_fma_f32 v[50:51], v[16:17], v[54:55], v[50:51]
	v_mov_b32_e32 v60, v53
	v_pk_fma_f32 v[50:51], v[20:21], v[60:61], v[50:51]
	v_add_f32_e32 v50, v56, v50
	v_add_f32_e32 v51, v50, v51
	v_mul_f32_e64 v50, |v51|, s4
	v_exp_f32_e32 v50, v50
	v_mov_b32_e32 v52, v64
	v_min_f32_e32 v51, 0, v51
	v_add_f32_e32 v50, 1.0, v50
	s_nop 1
	v_log_f32_e32 v64, v50
	v_mov_b32_e32 v50, v52
	ds_read_b128 v[52:55], v42 offset:35456
	ds_read_b128 v[56:59], v42 offset:35472
	v_sub_f32_e32 v50, v63, v50
	v_mul_f32_e32 v60, 0x3f317217, v64
	v_fma_f32 v65, v64, s36, -v60
	s_waitcnt lgkmcnt(1)
	v_mov_b32_e32 v60, v52
	s_waitcnt lgkmcnt(0)
	v_mov_b32_e32 v61, v56
	v_mov_b32_e32 v56, v53
	v_pk_mul_f32 v[52:53], v[26:27], v[56:57]
	v_mov_b32_e32 v56, v54
	v_pk_fma_f32 v[52:53], v[24:25], v[60:61], v[52:53]
	v_mov_b32_e32 v57, v58
	v_pk_fma_f32 v[56:57], v[22:23], v[56:57], v[52:53]
	v_mov_b32_e32 v58, v55
	ds_read_b128 v[52:55], v42 offset:35488
	ds_read_b128 v[60:63], v42 offset:35504
	v_pk_fma_f32 v[56:57], v[28:29], v[58:59], v[56:57]
	v_fmac_f32_e32 v65, 0x3377d1cf, v64
	v_add_f32_e32 v56, v2, v56
	v_add_f32_e32 v58, v56, v57
	s_waitcnt lgkmcnt(0)
	v_mov_b32_e32 v57, v60
	v_mov_b32_e32 v60, v53
	v_mov_b32_e32 v56, v52
	v_pk_mul_f32 v[52:53], v[18:19], v[60:61]
	v_fmac_f32_e32 v65, 0x3f317217, v64
	v_pk_fma_f32 v[52:53], v[14:15], v[56:57], v[52:53]
	v_mov_b32_e32 v56, v54
	v_mov_b32_e32 v57, v62
	v_pk_fma_f32 v[52:53], v[16:17], v[56:57], v[52:53]
	v_mov_b32_e32 v62, v55
	v_pk_fma_f32 v[52:53], v[20:21], v[62:63], v[52:53]
	v_add_f32_e32 v52, v58, v52
	v_add_f32_e32 v52, v52, v53
	v_mul_f32_e64 v53, |v52|, s4
	v_exp_f32_e32 v53, v53
	s_nop 0
	v_add_f32_e32 v53, 1.0, v53
	v_mov_b32_e32 v54, v65
	v_min_f32_e32 v65, 0, v52
	v_log_f32_e32 v64, v53
	v_mov_b32_e32 v53, v54
	v_sub_f32_e32 v51, v51, v53
	ds_read_b128 v[52:55], v42 offset:35520
	ds_read_b128 v[56:59], v42 offset:35536
	v_mul_f32_e32 v60, 0x3f317217, v64
	v_fma_f32 v66, v64, s36, -v60
	v_fmac_f32_e32 v66, 0x3377d1cf, v64
	s_waitcnt lgkmcnt(1)
	v_mov_b32_e32 v60, v52
	s_waitcnt lgkmcnt(0)
	v_mov_b32_e32 v61, v56
	v_mov_b32_e32 v56, v53
	v_pk_mul_f32 v[52:53], v[26:27], v[56:57]
	v_mov_b32_e32 v56, v54
	v_pk_fma_f32 v[52:53], v[24:25], v[60:61], v[52:53]
	v_mov_b32_e32 v57, v58
	v_pk_fma_f32 v[56:57], v[22:23], v[56:57], v[52:53]
	v_mov_b32_e32 v58, v55
	ds_read_b128 v[52:55], v42 offset:35552
	ds_read_b128 v[60:63], v42 offset:35568
	v_pk_fma_f32 v[56:57], v[28:29], v[58:59], v[56:57]
	v_fmac_f32_e32 v66, 0x3f317217, v64
	v_add_f32_e32 v56, v2, v56
	v_add_f32_e32 v58, v56, v57
	s_waitcnt lgkmcnt(0)
	v_mov_b32_e32 v57, v60
	v_mov_b32_e32 v60, v53
	v_mov_b32_e32 v56, v52
	v_pk_mul_f32 v[52:53], v[18:19], v[60:61]
	v_pk_fma_f32 v[52:53], v[14:15], v[56:57], v[52:53]
	v_mov_b32_e32 v56, v54
	v_mov_b32_e32 v57, v62
	v_pk_fma_f32 v[52:53], v[16:17], v[56:57], v[52:53]
	v_mov_b32_e32 v62, v55
	v_pk_fma_f32 v[52:53], v[20:21], v[62:63], v[52:53]
	v_add_f32_e32 v52, v58, v52
	v_add_f32_e32 v53, v52, v53
	v_mul_f32_e64 v52, |v53|, s4
	v_exp_f32_e32 v52, v52
	v_mov_b32_e32 v54, v66
	v_min_f32_e32 v53, 0, v53
	v_add_f32_e32 v52, 1.0, v52
	s_nop 1
	v_log_f32_e32 v66, v52
	v_mov_b32_e32 v52, v54
	ds_read_b128 v[54:57], v42 offset:35584
	ds_read_b128 v[58:61], v42 offset:35600
	v_sub_f32_e32 v52, v65, v52
	v_mul_f32_e32 v62, 0x3f317217, v66
	v_fma_f32 v67, v66, s36, -v62
	s_waitcnt lgkmcnt(1)
	v_mov_b32_e32 v62, v54
	s_waitcnt lgkmcnt(0)
; #define LAS __attribute__((address_space(3)))
; __device__ __forceinline__ void gla_bcum(KArgs a, int tid, int t0, int h, LAS float* segtot, LAS float* glrs, float (&bc)[32], float& tot) {
;     ...
;     for (int r = 0; r < 32; ++r) { const LAS f32x4* gp = (const LAS f32x4*)(glrs + (seg * 32 + r) * 16);
;         float z = bias;
; #pragma unroll
;         for (int q = 0; q < 4; ++q) { const f32x4 g = gp[q]; z += g[0] * w2r[4 * q] + g[1] * w2r[4 * q + 1] + g[2] * w2r[4 * q + 2] + g[3] * w2r[4 * q + 3]; }
;         const float la = (fminf(z, 0.f) - __logf(1.0f + __expf(-fabsf(z)))) * (1.0f / 16.0f);
;         run += la; bc[r] = run; }
	v_mov_b32_e32 v63, v58
	v_mov_b32_e32 v58, v55
	v_pk_mul_f32 v[54:55], v[26:27], v[58:59]
	v_mov_b32_e32 v58, v56
	v_pk_fma_f32 v[54:55], v[24:25], v[62:63], v[54:55]
	v_mov_b32_e32 v59, v60
	v_pk_fma_f32 v[58:59], v[22:23], v[58:59], v[54:55]
	v_mov_b32_e32 v60, v57
	ds_read_b128 v[54:57], v42 offset:35616
	ds_read_b128 v[62:65], v42 offset:35632
	v_pk_fma_f32 v[58:59], v[28:29], v[60:61], v[58:59]
	v_fmac_f32_e32 v67, 0x3377d1cf, v66
	v_add_f32_e32 v58, v2, v58
	v_add_f32_e32 v60, v58, v59
	s_waitcnt lgkmcnt(0)
	v_mov_b32_e32 v59, v62
	v_mov_b32_e32 v62, v55
	v_mov_b32_e32 v58, v54
	v_pk_mul_f32 v[54:55], v[18:19], v[62:63]
	v_fmac_f32_e32 v67, 0x3f317217, v66
	v_pk_fma_f32 v[54:55], v[14:15], v[58:59], v[54:55]
	v_mov_b32_e32 v58, v56
	v_mov_b32_e32 v59, v64
	v_pk_fma_f32 v[54:55], v[16:17], v[58:59], v[54:55]
	v_mov_b32_e32 v64, v57
	v_pk_fma_f32 v[54:55], v[20:21], v[64:65], v[54:55]
	v_add_f32_e32 v54, v60, v54
	v_add_f32_e32 v54, v54, v55
	v_mul_f32_e64 v55, |v54|, s4
	v_exp_f32_e32 v55, v55
	s_nop 0
	v_add_f32_e32 v55, 1.0, v55
	v_mov_b32_e32 v56, v67
	v_min_f32_e32 v67, 0, v54
	v_log_f32_e32 v66, v55
	v_mov_b32_e32 v55, v56
	v_sub_f32_e32 v53, v53, v55
	ds_read_b128 v[54:57], v42 offset:35648
	ds_read_b128 v[58:61], v42 offset:35664
	v_mul_f32_e32 v62, 0x3f317217, v66
	v_fma_f32 v68, v66, s36, -v62
	v_fmac_f32_e32 v68, 0x3377d1cf, v66
	s_waitcnt lgkmcnt(1)
	v_mov_b32_e32 v62, v54
	s_waitcnt lgkmcnt(0)
	v_mov_b32_e32 v63, v58
	v_mov_b32_e32 v58, v55
	v_pk_mul_f32 v[54:55], v[26:27], v[58:59]
	v_mov_b32_e32 v58, v56
	v_pk_fma_f32 v[54:55], v[24:25], v[62:63], v[54:55]
	v_mov_b32_e32 v59, v60
	v_pk_fma_f32 v[58:59], v[22:23], v[58:59], v[54:55]
	v_mov_b32_e32 v60, v57
	ds_read_b128 v[54:57], v42 offset:35680
	ds_read_b128 v[62:65], v42 offset:35696
	v_pk_fma_f32 v[58:59], v[28:29], v[60:61], v[58:59]
	v_fmac_f32_e32 v68, 0x3f317217, v66
	v_add_f32_e32 v58, v2, v58
	v_add_f32_e32 v60, v58, v59
	s_waitcnt lgkmcnt(0)
	v_mov_b32_e32 v59, v62
	v_mov_b32_e32 v62, v55
	v_mov_b32_e32 v58, v54
	v_pk_mul_f32 v[54:55], v[18:19], v[62:63]
	v_pk_fma_f32 v[54:55], v[14:15], v[58:59], v[54:55]
	v_mov_b32_e32 v58, v56
	v_mov_b32_e32 v59, v64
	v_pk_fma_f32 v[54:55], v[16:17], v[58:59], v[54:55]
	v_mov_b32_e32 v64, v57
	v_pk_fma_f32 v[54:55], v[20:21], v[64:65], v[54:55]
	v_add_f32_e32 v54, v60, v54
	v_add_f32_e32 v55, v54, v55
	v_mul_f32_e64 v54, |v55|, s4
	v_exp_f32_e32 v54, v54
	v_mov_b32_e32 v56, v68
	v_min_f32_e32 v55, 0, v55
	v_add_f32_e32 v54, 1.0, v54
	s_nop 1
	v_log_f32_e32 v68, v54
	v_mov_b32_e32 v54, v56
	ds_read_b128 v[56:59], v42 offset:35712
	ds_read_b128 v[60:63], v42 offset:35728
	v_sub_f32_e32 v54, v67, v54
	v_mul_f32_e32 v64, 0x3f317217, v68
	v_fma_f32 v69, v68, s36, -v64
	s_waitcnt lgkmcnt(1)
	v_mov_b32_e32 v64, v56
	s_waitcnt lgkmcnt(0)
	v_mov_b32_e32 v65, v60
	v_mov_b32_e32 v60, v57
	v_pk_mul_f32 v[56:57], v[26:27], v[60:61]
	v_mov_b32_e32 v60, v58
	v_pk_fma_f32 v[56:57], v[24:25], v[64:65], v[56:57]
	v_mov_b32_e32 v61, v62
	v_pk_fma_f32 v[60:61], v[22:23], v[60:61], v[56:57]
	v_mov_b32_e32 v62, v59
	ds_read_b128 v[56:59], v42 offset:35744
	ds_read_b128 v[64:67], v42 offset:35760
	v_pk_fma_f32 v[60:61], v[28:29], v[62:63], v[60:61]
	v_fmac_f32_e32 v69, 0x3377d1cf, v68
	v_add_f32_e32 v60, v2, v60
	v_add_f32_e32 v62, v60, v61
	s_waitcnt lgkmcnt(0)
	v_mov_b32_e32 v61, v64
	v_mov_b32_e32 v64, v57
	v_mov_b32_e32 v60, v56
	v_pk_mul_f32 v[56:57], v[18:19], v[64:65]
	v_fmac_f32_e32 v69, 0x3f317217, v68
	v_pk_fma_f32 v[56:57], v[14:15], v[60:61], v[56:57]
	v_mov_b32_e32 v60, v58
	v_mov_b32_e32 v61, v66
	v_pk_fma_f32 v[56:57], v[16:17], v[60:61], v[56:57]
	v_mov_b32_e32 v66, v59
	v_pk_fma_f32 v[56:57], v[20:21], v[66:67], v[56:57]
	v_add_f32_e32 v56, v62, v56
	v_add_f32_e32 v56, v56, v57
	v_mul_f32_e64 v57, |v56|, s4
	v_exp_f32_e32 v57, v57
	s_nop 0
	v_add_f32_e32 v57, 1.0, v57
	v_mov_b32_e32 v58, v69
	v_min_f32_e32 v69, 0, v56
	v_log_f32_e32 v68, v57
	v_mov_b32_e32 v57, v58
	v_sub_f32_e32 v55, v55, v57
	ds_read_b128 v[56:59], v42 offset:35776
	ds_read_b128 v[60:63], v42 offset:35792
	v_mul_f32_e32 v64, 0x3f317217, v68
	v_fma_f32 v70, v68, s36, -v64
	v_fmac_f32_e32 v70, 0x3377d1cf, v68
	s_waitcnt lgkmcnt(1)
	v_mov_b32_e32 v64, v56
	s_waitcnt lgkmcnt(0)
	v_mov_b32_e32 v65, v60
	v_mov_b32_e32 v60, v57
	v_pk_mul_f32 v[56:57], v[26:27], v[60:61]
	v_mov_b32_e32 v60, v58
	v_pk_fma_f32 v[56:57], v[24:25], v[64:65], v[56:57]
	v_mov_b32_e32 v61, v62
	v_pk_fma_f32 v[60:61], v[22:23], v[60:61], v[56:57]
	v_mov_b32_e32 v62, v59
	ds_read_b128 v[56:59], v42 offset:35808
	ds_read_b128 v[64:67], v42 offset:35824
	v_pk_fma_f32 v[60:61], v[28:29], v[62:63], v[60:61]
	v_fmac_f32_e32 v70, 0x3f317217, v68
	v_add_f32_e32 v60, v2, v60
	v_add_f32_e32 v62, v60, v61
	s_waitcnt lgkmcnt(0)
	v_mov_b32_e32 v61, v64
	v_mov_b32_e32 v64, v57
	v_mov_b32_e32 v60, v56
	v_pk_mul_f32 v[56:57], v[18:19], v[64:65]
	v_pk_fma_f32 v[56:57], v[14:15], v[60:61], v[56:57]
	v_mov_b32_e32 v60, v58
	v_mov_b32_e32 v61, v66
	v_pk_fma_f32 v[56:57], v[16:17], v[60:61], v[56:57]
	v_mov_b32_e32 v66, v59
	v_pk_fma_f32 v[56:57], v[20:21], v[66:67], v[56:57]
	v_add_f32_e32 v56, v62, v56
	v_add_f32_e32 v57, v56, v57
	v_mul_f32_e64 v56, |v57|, s4
	v_exp_f32_e32 v56, v56
	v_mov_b32_e32 v58, v70
	v_min_f32_e32 v57, 0, v57
	v_add_f32_e32 v56, 1.0, v56
	s_nop 1
	v_log_f32_e32 v70, v56
	v_mov_b32_e32 v56, v58
	ds_read_b128 v[58:61], v42 offset:35840
	ds_read_b128 v[62:65], v42 offset:35856
	v_sub_f32_e32 v56, v69, v56
	v_mul_f32_e32 v66, 0x3f317217, v70
	v_fma_f32 v71, v70, s36, -v66
	s_waitcnt lgkmcnt(1)
	v_mov_b32_e32 v66, v58
	s_waitcnt lgkmcnt(0)
; #define LAS __attribute__((address_space(3)))
; __device__ __forceinline__ void gla_bcum(KArgs a, int tid, int t0, int h, LAS float* segtot, LAS float* glrs, float (&bc)[32], float& tot) {
;     ...
;     for (int r = 0; r < 32; ++r) { const LAS f32x4* gp = (const LAS f32x4*)(glrs + (seg * 32 + r) * 16);
;         float z = bias;
; #pragma unroll
;         for (int q = 0; q < 4; ++q) { const f32x4 g = gp[q]; z += g[0] * w2r[4 * q] + g[1] * w2r[4 * q + 1] + g[2] * w2r[4 * q + 2] + g[3] * w2r[4 * q + 3]; }
;         const float la = (fminf(z, 0.f) - __logf(1.0f + __expf(-fabsf(z)))) * (1.0f / 16.0f);
;         run += la; bc[r] = run; }
	v_mov_b32_e32 v67, v62
	v_mov_b32_e32 v62, v59
	v_pk_mul_f32 v[58:59], v[26:27], v[62:63]
	v_mov_b32_e32 v62, v60
	v_pk_fma_f32 v[58:59], v[24:25], v[66:67], v[58:59]
	v_mov_b32_e32 v63, v64
	v_pk_fma_f32 v[62:63], v[22:23], v[62:63], v[58:59]
	v_mov_b32_e32 v64, v61
	ds_read_b128 v[58:61], v42 offset:35872
	ds_read_b128 v[66:69], v42 offset:35888
	v_pk_fma_f32 v[62:63], v[28:29], v[64:65], v[62:63]
	v_fmac_f32_e32 v71, 0x3377d1cf, v70
	v_add_f32_e32 v62, v2, v62
	v_add_f32_e32 v64, v62, v63
	s_waitcnt lgkmcnt(0)
	v_mov_b32_e32 v63, v66
	v_mov_b32_e32 v66, v59
	v_mov_b32_e32 v62, v58
	v_pk_mul_f32 v[58:59], v[18:19], v[66:67]
	v_fmac_f32_e32 v71, 0x3f317217, v70
	v_pk_fma_f32 v[58:59], v[14:15], v[62:63], v[58:59]
	v_mov_b32_e32 v62, v60
	v_mov_b32_e32 v63, v68
	v_pk_fma_f32 v[58:59], v[16:17], v[62:63], v[58:59]
	v_mov_b32_e32 v68, v61
	v_pk_fma_f32 v[58:59], v[20:21], v[68:69], v[58:59]
	v_add_f32_e32 v58, v64, v58
	v_add_f32_e32 v58, v58, v59
	v_mul_f32_e64 v59, |v58|, s4
	v_exp_f32_e32 v59, v59
	s_nop 0
	v_add_f32_e32 v59, 1.0, v59
	v_mov_b32_e32 v60, v71
	v_min_f32_e32 v71, 0, v58
	v_log_f32_e32 v70, v59
	v_mov_b32_e32 v59, v60
	v_sub_f32_e32 v57, v57, v59
	ds_read_b128 v[58:61], v42 offset:35904
	ds_read_b128 v[62:65], v42 offset:35920
	v_mul_f32_e32 v66, 0x3f317217, v70
	v_fma_f32 v72, v70, s36, -v66
	v_fmac_f32_e32 v72, 0x3377d1cf, v70
	s_waitcnt lgkmcnt(1)
	v_mov_b32_e32 v66, v58
	s_waitcnt lgkmcnt(0)
	v_mov_b32_e32 v67, v62
	v_mov_b32_e32 v62, v59
	v_pk_mul_f32 v[58:59], v[26:27], v[62:63]
	v_mov_b32_e32 v62, v60
	v_pk_fma_f32 v[58:59], v[24:25], v[66:67], v[58:59]
	v_mov_b32_e32 v63, v64
	v_pk_fma_f32 v[62:63], v[22:23], v[62:63], v[58:59]
	v_mov_b32_e32 v64, v61
	ds_read_b128 v[58:61], v42 offset:35936
	ds_read_b128 v[66:69], v42 offset:35952
	v_pk_fma_f32 v[62:63], v[28:29], v[64:65], v[62:63]
	v_fmac_f32_e32 v72, 0x3f317217, v70
	v_add_f32_e32 v62, v2, v62
	v_add_f32_e32 v64, v62, v63
	s_waitcnt lgkmcnt(0)
	v_mov_b32_e32 v63, v66
	v_mov_b32_e32 v66, v59
	v_mov_b32_e32 v62, v58
	v_pk_mul_f32 v[58:59], v[18:19], v[66:67]
	v_pk_fma_f32 v[58:59], v[14:15], v[62:63], v[58:59]
	v_mov_b32_e32 v62, v60
	v_mov_b32_e32 v63, v68
	v_pk_fma_f32 v[58:59], v[16:17], v[62:63], v[58:59]
	v_mov_b32_e32 v68, v61
	v_pk_fma_f32 v[58:59], v[20:21], v[68:69], v[58:59]
	v_add_f32_e32 v58, v64, v58
	v_add_f32_e32 v59, v58, v59
	v_mul_f32_e64 v58, |v59|, s4
	v_exp_f32_e32 v58, v58
	v_mov_b32_e32 v60, v72
	v_min_f32_e32 v59, 0, v59
	v_add_f32_e32 v58, 1.0, v58
	s_nop 1
	v_log_f32_e32 v72, v58
	v_mov_b32_e32 v58, v60
	ds_read_b128 v[60:63], v42 offset:35968
	ds_read_b128 v[64:67], v42 offset:35984
	v_sub_f32_e32 v58, v71, v58
	v_mul_f32_e32 v68, 0x3f317217, v72
	v_fma_f32 v73, v72, s36, -v68
	s_waitcnt lgkmcnt(1)
	v_mov_b32_e32 v68, v60
	s_waitcnt lgkmcnt(0)
	v_mov_b32_e32 v69, v64
	v_mov_b32_e32 v64, v61
	v_pk_mul_f32 v[60:61], v[26:27], v[64:65]
	v_mov_b32_e32 v64, v62
	v_pk_fma_f32 v[60:61], v[24:25], v[68:69], v[60:61]
	v_mov_b32_e32 v65, v66
	v_pk_fma_f32 v[64:65], v[22:23], v[64:65], v[60:61]
	v_mov_b32_e32 v66, v63
	ds_read_b128 v[60:63], v42 offset:36000
	ds_read_b128 v[68:71], v42 offset:36016
	v_pk_fma_f32 v[64:65], v[28:29], v[66:67], v[64:65]
	v_fmac_f32_e32 v73, 0x3377d1cf, v72
	v_add_f32_e32 v64, v2, v64
	v_add_f32_e32 v66, v64, v65
	s_waitcnt lgkmcnt(0)
	v_mov_b32_e32 v65, v68
	v_mov_b32_e32 v68, v61
	v_mov_b32_e32 v64, v60
	v_pk_mul_f32 v[60:61], v[18:19], v[68:69]
	v_fmac_f32_e32 v73, 0x3f317217, v72
	v_pk_fma_f32 v[60:61], v[14:15], v[64:65], v[60:61]
	v_mov_b32_e32 v64, v62
	v_mov_b32_e32 v65, v70
	v_pk_fma_f32 v[60:61], v[16:17], v[64:65], v[60:61]
	v_mov_b32_e32 v70, v63
	v_pk_fma_f32 v[60:61], v[20:21], v[70:71], v[60:61]
	v_add_f32_e32 v60, v66, v60
	v_add_f32_e32 v60, v60, v61
	v_mul_f32_e64 v61, |v60|, s4
	v_exp_f32_e32 v61, v61
	s_nop 0
	v_add_f32_e32 v61, 1.0, v61
	v_mov_b32_e32 v62, v73
	v_min_f32_e32 v73, 0, v60
	v_log_f32_e32 v72, v61
	v_mov_b32_e32 v61, v62
	v_sub_f32_e32 v59, v59, v61
	ds_read_b128 v[60:63], v42 offset:36032
	ds_read_b128 v[64:67], v42 offset:36048
	v_mul_f32_e32 v68, 0x3f317217, v72
	v_fma_f32 v74, v72, s36, -v68
	v_fmac_f32_e32 v74, 0x3377d1cf, v72
	s_waitcnt lgkmcnt(1)
	v_mov_b32_e32 v68, v60
	s_waitcnt lgkmcnt(0)
	v_mov_b32_e32 v69, v64
	v_mov_b32_e32 v64, v61
	v_pk_mul_f32 v[60:61], v[26:27], v[64:65]
	v_mov_b32_e32 v64, v62
	v_pk_fma_f32 v[60:61], v[24:25], v[68:69], v[60:61]
	v_mov_b32_e32 v65, v66
	v_pk_fma_f32 v[64:65], v[22:23], v[64:65], v[60:61]
	v_mov_b32_e32 v66, v63
	ds_read_b128 v[60:63], v42 offset:36064
	ds_read_b128 v[68:71], v42 offset:36080
	v_pk_fma_f32 v[64:65], v[28:29], v[66:67], v[64:65]
	v_fmac_f32_e32 v74, 0x3f317217, v72
	v_add_f32_e32 v64, v2, v64
	v_add_f32_e32 v66, v64, v65
	s_waitcnt lgkmcnt(0)
	v_mov_b32_e32 v65, v68
	v_mov_b32_e32 v68, v61
	v_mov_b32_e32 v64, v60
	v_pk_mul_f32 v[60:61], v[18:19], v[68:69]
	v_pk_fma_f32 v[60:61], v[14:15], v[64:65], v[60:61]
	v_mov_b32_e32 v64, v62
	v_mov_b32_e32 v65, v70
	v_pk_fma_f32 v[60:61], v[16:17], v[64:65], v[60:61]
	v_mov_b32_e32 v70, v63
	v_pk_fma_f32 v[60:61], v[20:21], v[70:71], v[60:61]
	v_add_f32_e32 v60, v66, v60
	v_add_f32_e32 v61, v60, v61
	v_mul_f32_e64 v60, |v61|, s4
	v_exp_f32_e32 v60, v60
	v_mov_b32_e32 v62, v74
	v_min_f32_e32 v61, 0, v61
	v_add_f32_e32 v60, 1.0, v60
	s_nop 1
	v_log_f32_e32 v74, v60
	v_mov_b32_e32 v60, v62
	ds_read_b128 v[62:65], v42 offset:36096
	ds_read_b128 v[66:69], v42 offset:36112
	v_sub_f32_e32 v60, v73, v60
	v_mul_f32_e32 v70, 0x3f317217, v74
	v_fma_f32 v75, v74, s36, -v70
	s_waitcnt lgkmcnt(1)
	v_mov_b32_e32 v70, v62
	s_waitcnt lgkmcnt(0)
; #define LAS __attribute__((address_space(3)))
; __device__ __forceinline__ void gla_bcum(KArgs a, int tid, int t0, int h, LAS float* segtot, LAS float* glrs, float (&bc)[32], float& tot) {
;     ...
;     for (int r = 0; r < 32; ++r) { const LAS f32x4* gp = (const LAS f32x4*)(glrs + (seg * 32 + r) * 16);
;         float z = bias;
; #pragma unroll
;         for (int q = 0; q < 4; ++q) { const f32x4 g = gp[q]; z += g[0] * w2r[4 * q] + g[1] * w2r[4 * q + 1] + g[2] * w2r[4 * q + 2] + g[3] * w2r[4 * q + 3]; }
;         const float la = (fminf(z, 0.f) - __logf(1.0f + __expf(-fabsf(z)))) * (1.0f / 16.0f);
;         run += la; bc[r] = run; }
	v_mov_b32_e32 v71, v66
	v_mov_b32_e32 v66, v63
	v_pk_mul_f32 v[62:63], v[26:27], v[66:67]
	v_mov_b32_e32 v66, v64
	v_pk_fma_f32 v[62:63], v[24:25], v[70:71], v[62:63]
	v_mov_b32_e32 v67, v68
	v_pk_fma_f32 v[66:67], v[22:23], v[66:67], v[62:63]
	v_mov_b32_e32 v68, v65
	ds_read_b128 v[62:65], v42 offset:36128
	ds_read_b128 v[70:73], v42 offset:36144
	v_pk_fma_f32 v[66:67], v[28:29], v[68:69], v[66:67]
	v_fmac_f32_e32 v75, 0x3377d1cf, v74
	v_add_f32_e32 v66, v2, v66
	v_add_f32_e32 v68, v66, v67
	s_waitcnt lgkmcnt(0)
	v_mov_b32_e32 v67, v70
	v_mov_b32_e32 v70, v63
	v_mov_b32_e32 v66, v62
	v_pk_mul_f32 v[62:63], v[18:19], v[70:71]
	v_fmac_f32_e32 v75, 0x3f317217, v74
	v_pk_fma_f32 v[62:63], v[14:15], v[66:67], v[62:63]
	v_mov_b32_e32 v66, v64
	v_mov_b32_e32 v67, v72
	v_pk_fma_f32 v[62:63], v[16:17], v[66:67], v[62:63]
	v_mov_b32_e32 v72, v65
	v_pk_fma_f32 v[62:63], v[20:21], v[72:73], v[62:63]
	v_add_f32_e32 v62, v68, v62
	v_add_f32_e32 v62, v62, v63
	v_mul_f32_e64 v63, |v62|, s4
	v_exp_f32_e32 v63, v63
	s_nop 0
	v_add_f32_e32 v63, 1.0, v63
	v_mov_b32_e32 v64, v75
	v_min_f32_e32 v75, 0, v62
	v_log_f32_e32 v74, v63
	v_mov_b32_e32 v63, v64
	v_sub_f32_e32 v61, v61, v63
	ds_read_b128 v[62:65], v42 offset:36160
	ds_read_b128 v[66:69], v42 offset:36176
	v_mul_f32_e32 v70, 0x3f317217, v74
	v_fma_f32 v76, v74, s36, -v70
	v_fmac_f32_e32 v76, 0x3377d1cf, v74
	s_waitcnt lgkmcnt(1)
	v_mov_b32_e32 v70, v62
	s_waitcnt lgkmcnt(0)
	v_mov_b32_e32 v71, v66
	v_mov_b32_e32 v66, v63
	v_pk_mul_f32 v[62:63], v[26:27], v[66:67]
	v_mov_b32_e32 v66, v64
	v_pk_fma_f32 v[62:63], v[24:25], v[70:71], v[62:63]
	v_mov_b32_e32 v67, v68
	v_pk_fma_f32 v[66:67], v[22:23], v[66:67], v[62:63]
	v_mov_b32_e32 v68, v65
	ds_read_b128 v[62:65], v42 offset:36192
	ds_read_b128 v[70:73], v42 offset:36208
	v_pk_fma_f32 v[66:67], v[28:29], v[68:69], v[66:67]
	v_fmac_f32_e32 v76, 0x3f317217, v74
	v_add_f32_e32 v66, v2, v66
	v_add_f32_e32 v68, v66, v67
	s_waitcnt lgkmcnt(0)
	v_mov_b32_e32 v67, v70
	v_mov_b32_e32 v70, v63
	v_mov_b32_e32 v66, v62
	v_pk_mul_f32 v[62:63], v[18:19], v[70:71]
	v_pk_fma_f32 v[62:63], v[14:15], v[66:67], v[62:63]
	v_mov_b32_e32 v66, v64
	v_mov_b32_e32 v67, v72
	v_pk_fma_f32 v[62:63], v[16:17], v[66:67], v[62:63]
	v_mov_b32_e32 v72, v65
	v_pk_fma_f32 v[62:63], v[20:21], v[72:73], v[62:63]
	v_add_f32_e32 v62, v68, v62
	v_add_f32_e32 v63, v62, v63
	v_mul_f32_e64 v62, |v63|, s4
	v_exp_f32_e32 v62, v62
	v_mov_b32_e32 v64, v76
	v_min_f32_e32 v63, 0, v63
	v_add_f32_e32 v62, 1.0, v62
	s_nop 1
	v_log_f32_e32 v76, v62
	v_mov_b32_e32 v62, v64
	ds_read_b128 v[64:67], v42 offset:36224
	ds_read_b128 v[68:71], v42 offset:36240
	v_sub_f32_e32 v62, v75, v62
	v_mul_f32_e32 v72, 0x3f317217, v76
	v_fma_f32 v77, v76, s36, -v72
	s_waitcnt lgkmcnt(1)
	v_mov_b32_e32 v72, v64
	s_waitcnt lgkmcnt(0)
	v_mov_b32_e32 v73, v68
	v_mov_b32_e32 v68, v65
	v_pk_mul_f32 v[64:65], v[26:27], v[68:69]
	v_mov_b32_e32 v68, v66
	v_pk_fma_f32 v[64:65], v[24:25], v[72:73], v[64:65]
	v_mov_b32_e32 v69, v70
	v_pk_fma_f32 v[68:69], v[22:23], v[68:69], v[64:65]
	v_mov_b32_e32 v70, v67
	ds_read_b128 v[64:67], v42 offset:36256
	ds_read_b128 v[72:75], v42 offset:36272
	v_pk_fma_f32 v[68:69], v[28:29], v[70:71], v[68:69]
	v_fmac_f32_e32 v77, 0x3377d1cf, v76
	v_add_f32_e32 v68, v2, v68
	v_add_f32_e32 v70, v68, v69
	s_waitcnt lgkmcnt(0)
	v_mov_b32_e32 v69, v72
	v_mov_b32_e32 v72, v65
	v_mov_b32_e32 v68, v64
	v_pk_mul_f32 v[64:65], v[18:19], v[72:73]
	v_fmac_f32_e32 v77, 0x3f317217, v76
	v_pk_fma_f32 v[64:65], v[14:15], v[68:69], v[64:65]
	v_mov_b32_e32 v68, v66
	v_mov_b32_e32 v69, v74
	v_pk_fma_f32 v[64:65], v[16:17], v[68:69], v[64:65]
	v_mov_b32_e32 v74, v67
	v_pk_fma_f32 v[64:65], v[20:21], v[74:75], v[64:65]
	v_add_f32_e32 v64, v70, v64
	v_add_f32_e32 v64, v64, v65
	v_mul_f32_e64 v65, |v64|, s4
	v_exp_f32_e32 v65, v65
	s_nop 0
	v_add_f32_e32 v65, 1.0, v65
	v_mov_b32_e32 v66, v77
	v_min_f32_e32 v77, 0, v64
	v_log_f32_e32 v76, v65
	v_mov_b32_e32 v65, v66
	v_sub_f32_e32 v63, v63, v65
	ds_read_b128 v[64:67], v42 offset:36288
	ds_read_b128 v[68:71], v42 offset:36304
	v_mul_f32_e32 v72, 0x3f317217, v76
	v_fma_f32 v78, v76, s36, -v72
	v_fmac_f32_e32 v78, 0x3377d1cf, v76
	s_waitcnt lgkmcnt(1)
	v_mov_b32_e32 v72, v64
	s_waitcnt lgkmcnt(0)
	v_mov_b32_e32 v73, v68
	v_mov_b32_e32 v68, v65
	v_pk_mul_f32 v[64:65], v[26:27], v[68:69]
	v_mov_b32_e32 v68, v66
	v_pk_fma_f32 v[64:65], v[24:25], v[72:73], v[64:65]
	v_mov_b32_e32 v69, v70
	v_pk_fma_f32 v[68:69], v[22:23], v[68:69], v[64:65]
	v_mov_b32_e32 v70, v67
	ds_read_b128 v[64:67], v42 offset:36320
	ds_read_b128 v[72:75], v42 offset:36336
	v_pk_fma_f32 v[68:69], v[28:29], v[70:71], v[68:69]
	v_fmac_f32_e32 v78, 0x3f317217, v76
	v_add_f32_e32 v68, v2, v68
	v_add_f32_e32 v70, v68, v69
	s_waitcnt lgkmcnt(0)
	v_mov_b32_e32 v69, v72
	v_mov_b32_e32 v72, v65
	v_mov_b32_e32 v68, v64
	v_pk_mul_f32 v[64:65], v[18:19], v[72:73]
	v_pk_fma_f32 v[64:65], v[14:15], v[68:69], v[64:65]
	v_mov_b32_e32 v68, v66
	v_mov_b32_e32 v69, v74
	v_pk_fma_f32 v[64:65], v[16:17], v[68:69], v[64:65]
	v_mov_b32_e32 v74, v67
	v_pk_fma_f32 v[64:65], v[20:21], v[74:75], v[64:65]
	v_add_f32_e32 v64, v70, v64
	v_add_f32_e32 v65, v64, v65
	v_mul_f32_e64 v64, |v65|, s4
	v_exp_f32_e32 v64, v64
	v_mov_b32_e32 v66, v78
	v_min_f32_e32 v65, 0, v65
	v_add_f32_e32 v64, 1.0, v64
	s_nop 1
	v_log_f32_e32 v78, v64
	v_mov_b32_e32 v64, v66
	ds_read_b128 v[66:69], v42 offset:36352
	ds_read_b128 v[70:73], v42 offset:36368
	v_sub_f32_e32 v64, v77, v64
	v_mul_f32_e32 v74, 0x3f317217, v78
	v_fma_f32 v79, v78, s36, -v74
	s_waitcnt lgkmcnt(1)
	v_mov_b32_e32 v74, v66
	s_waitcnt lgkmcnt(0)
; #define LAS __attribute__((address_space(3)))
; __device__ __forceinline__ void gla_bcum(KArgs a, int tid, int t0, int h, LAS float* segtot, LAS float* glrs, float (&bc)[32], float& tot) {
;     ...
;     for (int r = 0; r < 32; ++r) { const LAS f32x4* gp = (const LAS f32x4*)(glrs + (seg * 32 + r) * 16);
;         float z = bias;
; #pragma unroll
;         for (int q = 0; q < 4; ++q) { const f32x4 g = gp[q]; z += g[0] * w2r[4 * q] + g[1] * w2r[4 * q + 1] + g[2] * w2r[4 * q + 2] + g[3] * w2r[4 * q + 3]; }
;         const float la = (fminf(z, 0.f) - __logf(1.0f + __expf(-fabsf(z)))) * (1.0f / 16.0f);
;         run += la; bc[r] = run; }
	v_mov_b32_e32 v75, v70
	v_mov_b32_e32 v70, v67
	v_pk_mul_f32 v[66:67], v[26:27], v[70:71]
	v_mov_b32_e32 v70, v68
	v_pk_fma_f32 v[66:67], v[24:25], v[74:75], v[66:67]
	v_mov_b32_e32 v71, v72
	v_pk_fma_f32 v[70:71], v[22:23], v[70:71], v[66:67]
	v_mov_b32_e32 v72, v69
	ds_read_b128 v[66:69], v42 offset:36384
	ds_read_b128 v[74:77], v42 offset:36400
	v_pk_fma_f32 v[70:71], v[28:29], v[72:73], v[70:71]
	v_fmac_f32_e32 v79, 0x3377d1cf, v78
	v_add_f32_e32 v70, v2, v70
	v_add_f32_e32 v72, v70, v71
	s_waitcnt lgkmcnt(0)
	v_mov_b32_e32 v71, v74
	v_mov_b32_e32 v74, v67
	v_mov_b32_e32 v70, v66
	v_pk_mul_f32 v[66:67], v[18:19], v[74:75]
	v_fmac_f32_e32 v79, 0x3f317217, v78
	v_pk_fma_f32 v[66:67], v[14:15], v[70:71], v[66:67]
	v_mov_b32_e32 v70, v68
	v_mov_b32_e32 v71, v76
	v_pk_fma_f32 v[66:67], v[16:17], v[70:71], v[66:67]
	v_mov_b32_e32 v76, v69
	v_pk_fma_f32 v[66:67], v[20:21], v[76:77], v[66:67]
	v_add_f32_e32 v66, v72, v66
	v_add_f32_e32 v66, v66, v67
	v_mul_f32_e64 v67, |v66|, s4
	v_exp_f32_e32 v67, v67
	s_nop 0
	v_add_f32_e32 v67, 1.0, v67
	v_mov_b32_e32 v68, v79
	v_min_f32_e32 v79, 0, v66
	v_log_f32_e32 v78, v67
	v_mov_b32_e32 v67, v68
	v_sub_f32_e32 v65, v65, v67
	ds_read_b128 v[66:69], v42 offset:36416
	ds_read_b128 v[70:73], v42 offset:36432
	v_mul_f32_e32 v74, 0x3f317217, v78
	v_fma_f32 v80, v78, s36, -v74
	v_fmac_f32_e32 v80, 0x3377d1cf, v78
	s_waitcnt lgkmcnt(1)
	v_mov_b32_e32 v74, v66
	s_waitcnt lgkmcnt(0)
	v_mov_b32_e32 v75, v70
	v_mov_b32_e32 v70, v67
	v_pk_mul_f32 v[66:67], v[26:27], v[70:71]
	v_mov_b32_e32 v70, v68
	v_pk_fma_f32 v[66:67], v[24:25], v[74:75], v[66:67]
	v_mov_b32_e32 v71, v72
	v_pk_fma_f32 v[70:71], v[22:23], v[70:71], v[66:67]
	v_mov_b32_e32 v72, v69
	ds_read_b128 v[66:69], v42 offset:36448
	ds_read_b128 v[74:77], v42 offset:36464
	v_pk_fma_f32 v[70:71], v[28:29], v[72:73], v[70:71]
	v_fmac_f32_e32 v80, 0x3f317217, v78
	v_add_f32_e32 v70, v2, v70
	v_add_f32_e32 v72, v70, v71
	s_waitcnt lgkmcnt(0)
	v_mov_b32_e32 v71, v74
	v_mov_b32_e32 v74, v67
	v_mov_b32_e32 v70, v66
	v_pk_mul_f32 v[66:67], v[18:19], v[74:75]
	v_pk_fma_f32 v[66:67], v[14:15], v[70:71], v[66:67]
	v_mov_b32_e32 v70, v68
	v_mov_b32_e32 v71, v76
	v_pk_fma_f32 v[66:67], v[16:17], v[70:71], v[66:67]
	v_mov_b32_e32 v76, v69
	v_pk_fma_f32 v[66:67], v[20:21], v[76:77], v[66:67]
	v_add_f32_e32 v66, v72, v66
	v_add_f32_e32 v66, v66, v67
	v_mul_f32_e64 v67, |v66|, s4
	v_exp_f32_e32 v67, v67
	v_mov_b32_e32 v68, v80
	v_min_f32_e32 v80, 0, v66
	v_add_f32_e32 v67, 1.0, v67
	s_nop 1
	v_log_f32_e32 v78, v67
	v_mov_b32_e32 v67, v68
	v_sub_f32_e32 v79, v79, v67
	ds_read_b128 v[66:69], v42 offset:36480
	ds_read_b128 v[70:73], v42 offset:36496
	v_mul_f32_e32 v74, 0x3f317217, v78
	v_fma_f32 v81, v78, s36, -v74
	v_fmac_f32_e32 v81, 0x3377d1cf, v78
	s_waitcnt lgkmcnt(1)
	v_mov_b32_e32 v74, v66
	s_waitcnt lgkmcnt(0)
	v_mov_b32_e32 v75, v70
	v_mov_b32_e32 v70, v67
	v_pk_mul_f32 v[66:67], v[26:27], v[70:71]
	v_mov_b32_e32 v70, v68
	v_pk_fma_f32 v[66:67], v[24:25], v[74:75], v[66:67]
	v_mov_b32_e32 v71, v72
	v_pk_fma_f32 v[70:71], v[22:23], v[70:71], v[66:67]
	v_mov_b32_e32 v72, v69
	ds_read_b128 v[66:69], v42 offset:36512
	ds_read_b128 v[74:77], v42 offset:36528
	v_pk_fma_f32 v[70:71], v[28:29], v[72:73], v[70:71]
	v_fmac_f32_e32 v81, 0x3f317217, v78
	v_add_f32_e32 v70, v2, v70
	v_add_f32_e32 v72, v70, v71
	s_waitcnt lgkmcnt(0)
	v_mov_b32_e32 v71, v74
	v_mov_b32_e32 v74, v67
	v_mov_b32_e32 v70, v66
	v_pk_mul_f32 v[66:67], v[18:19], v[74:75]
	v_pk_fma_f32 v[66:67], v[14:15], v[70:71], v[66:67]
	v_mov_b32_e32 v70, v68
	v_mov_b32_e32 v71, v76
	v_pk_fma_f32 v[66:67], v[16:17], v[70:71], v[66:67]
	v_mov_b32_e32 v76, v69
	v_pk_fma_f32 v[66:67], v[20:21], v[76:77], v[66:67]
	v_add_f32_e32 v66, v72, v66
	v_add_f32_e32 v66, v66, v67
	v_mul_f32_e64 v67, |v66|, s4
	v_exp_f32_e32 v67, v67
	v_mov_b32_e32 v68, v81
	v_min_f32_e32 v81, 0, v66
	v_add_f32_e32 v67, 1.0, v67
	s_nop 1
	v_log_f32_e32 v78, v67
	v_mov_b32_e32 v67, v68
	v_sub_f32_e32 v80, v80, v67
	ds_read_b128 v[66:69], v42 offset:36544
	ds_read_b128 v[70:73], v42 offset:36560
	v_mul_f32_e32 v74, 0x3f317217, v78
	v_fma_f32 v82, v78, s36, -v74
	v_fmac_f32_e32 v82, 0x3377d1cf, v78
	s_waitcnt lgkmcnt(1)
	v_mov_b32_e32 v74, v66
	s_waitcnt lgkmcnt(0)
	v_mov_b32_e32 v75, v70
	v_mov_b32_e32 v70, v67
	v_pk_mul_f32 v[66:67], v[26:27], v[70:71]
	v_mov_b32_e32 v70, v68
	v_pk_fma_f32 v[66:67], v[24:25], v[74:75], v[66:67]
	v_mov_b32_e32 v71, v72
	v_pk_fma_f32 v[70:71], v[22:23], v[70:71], v[66:67]
	v_mov_b32_e32 v72, v69
	ds_read_b128 v[66:69], v42 offset:36576
	ds_read_b128 v[74:77], v42 offset:36592
	v_pk_fma_f32 v[70:71], v[28:29], v[72:73], v[70:71]
	v_fmac_f32_e32 v82, 0x3f317217, v78
	v_add_f32_e32 v70, v2, v70
	v_add_f32_e32 v72, v70, v71
	s_waitcnt lgkmcnt(0)
	v_mov_b32_e32 v71, v74
	v_mov_b32_e32 v74, v67
	v_mov_b32_e32 v70, v66
	v_pk_mul_f32 v[66:67], v[18:19], v[74:75]
	v_pk_fma_f32 v[66:67], v[14:15], v[70:71], v[66:67]
	v_mov_b32_e32 v70, v68
	v_mov_b32_e32 v71, v76
	v_pk_fma_f32 v[66:67], v[16:17], v[70:71], v[66:67]
	v_mov_b32_e32 v76, v69
	v_pk_fma_f32 v[66:67], v[20:21], v[76:77], v[66:67]
	v_add_f32_e32 v66, v72, v66
	v_add_f32_e32 v66, v66, v67
	v_mul_f32_e64 v67, |v66|, s4
	v_exp_f32_e32 v67, v67
	v_mov_b32_e32 v68, v82
	v_min_f32_e32 v82, 0, v66
	v_add_f32_e32 v67, 1.0, v67
	s_nop 1
	v_log_f32_e32 v78, v67
	v_mov_b32_e32 v67, v68
	v_sub_f32_e32 v81, v81, v67
	ds_read_b128 v[66:69], v42 offset:36608
	ds_read_b128 v[70:73], v42 offset:36624
	v_mul_f32_e32 v74, 0x3f317217, v78
	v_fma_f32 v83, v78, s36, -v74
	v_fmac_f32_e32 v83, 0x3377d1cf, v78
	s_waitcnt lgkmcnt(1)
	v_mov_b32_e32 v74, v66
	s_waitcnt lgkmcnt(0)
; #define LAS __attribute__((address_space(3)))
; __device__ __forceinline__ void gla_bcum(KArgs a, int tid, int t0, int h, LAS float* segtot, LAS float* glrs, float (&bc)[32], float& tot) {
;     ...
;     for (int r = 0; r < 32; ++r) { const LAS f32x4* gp = (const LAS f32x4*)(glrs + (seg * 32 + r) * 16);
;         float z = bias;
; #pragma unroll
;         for (int q = 0; q < 4; ++q) { const f32x4 g = gp[q]; z += g[0] * w2r[4 * q] + g[1] * w2r[4 * q + 1] + g[2] * w2r[4 * q + 2] + g[3] * w2r[4 * q + 3]; }
;         const float la = (fminf(z, 0.f) - __logf(1.0f + __expf(-fabsf(z)))) * (1.0f / 16.0f);
;         run += la; bc[r] = run; }
;     segtot[seg * 128 + d] = run;
;     __syncthreads();
	v_mov_b32_e32 v75, v70
	v_mov_b32_e32 v70, v67
	v_pk_mul_f32 v[66:67], v[26:27], v[70:71]
	v_mov_b32_e32 v70, v68
	v_pk_fma_f32 v[66:67], v[24:25], v[74:75], v[66:67]
	v_mov_b32_e32 v71, v72
	v_pk_fma_f32 v[70:71], v[22:23], v[70:71], v[66:67]
	v_mov_b32_e32 v72, v69
	ds_read_b128 v[66:69], v42 offset:36640
	ds_read_b128 v[74:77], v42 offset:36656
	v_pk_fma_f32 v[70:71], v[28:29], v[72:73], v[70:71]
	v_fmac_f32_e32 v83, 0x3f317217, v78
	v_add_f32_e32 v70, v2, v70
	v_add_f32_e32 v72, v70, v71
	s_waitcnt lgkmcnt(0)
	v_mov_b32_e32 v71, v74
	v_mov_b32_e32 v74, v67
	v_mov_b32_e32 v70, v66
	v_pk_mul_f32 v[66:67], v[18:19], v[74:75]
	v_pk_fma_f32 v[66:67], v[14:15], v[70:71], v[66:67]
	v_mov_b32_e32 v70, v68
	v_mov_b32_e32 v71, v76
	v_pk_fma_f32 v[66:67], v[16:17], v[70:71], v[66:67]
	v_mov_b32_e32 v76, v69
	v_pk_fma_f32 v[66:67], v[20:21], v[76:77], v[66:67]
	v_add_f32_e32 v66, v72, v66
	v_add_f32_e32 v66, v66, v67
	v_mul_f32_e64 v67, |v66|, s4
	v_exp_f32_e32 v67, v67
	v_mov_b32_e32 v68, v83
	v_min_f32_e32 v83, 0, v66
	v_add_f32_e32 v67, 1.0, v67
	s_nop 1
	v_log_f32_e32 v78, v67
	v_mov_b32_e32 v67, v68
	v_sub_f32_e32 v82, v82, v67
	ds_read_b128 v[66:69], v42 offset:36672
	ds_read_b128 v[70:73], v42 offset:36688
	v_mul_f32_e32 v74, 0x3f317217, v78
	v_fma_f32 v84, v78, s36, -v74
	v_fmac_f32_e32 v84, 0x3377d1cf, v78
	s_waitcnt lgkmcnt(1)
	v_mov_b32_e32 v74, v66
	s_waitcnt lgkmcnt(0)
	v_mov_b32_e32 v75, v70
	v_mov_b32_e32 v70, v67
	v_pk_mul_f32 v[66:67], v[26:27], v[70:71]
	v_mov_b32_e32 v70, v68
	v_pk_fma_f32 v[66:67], v[24:25], v[74:75], v[66:67]
	v_mov_b32_e32 v71, v72
	v_pk_fma_f32 v[70:71], v[22:23], v[70:71], v[66:67]
	v_mov_b32_e32 v72, v69
	ds_read_b128 v[66:69], v42 offset:36704
	ds_read_b128 v[74:77], v42 offset:36720
	v_pk_fma_f32 v[70:71], v[28:29], v[72:73], v[70:71]
	v_fmac_f32_e32 v84, 0x3f317217, v78
	v_add_f32_e32 v70, v2, v70
	v_add_f32_e32 v72, v70, v71
	s_waitcnt lgkmcnt(0)
	v_mov_b32_e32 v71, v74
	v_mov_b32_e32 v74, v67
	v_mov_b32_e32 v70, v66
	v_pk_mul_f32 v[66:67], v[18:19], v[74:75]
	v_pk_fma_f32 v[66:67], v[14:15], v[70:71], v[66:67]
	v_mov_b32_e32 v70, v68
	v_mov_b32_e32 v71, v76
	v_pk_fma_f32 v[66:67], v[16:17], v[70:71], v[66:67]
	v_mov_b32_e32 v76, v69
	v_pk_fma_f32 v[66:67], v[20:21], v[76:77], v[66:67]
	v_add_f32_e32 v66, v72, v66
	v_add_f32_e32 v66, v66, v67
	v_mul_f32_e64 v67, |v66|, s4
	v_exp_f32_e32 v67, v67
	v_mov_b32_e32 v68, v84
	v_min_f32_e32 v84, 0, v66
	v_add_f32_e32 v67, 1.0, v67
	s_nop 1
	v_log_f32_e32 v78, v67
	v_mov_b32_e32 v67, v68
	v_sub_f32_e32 v83, v83, v67
	ds_read_b128 v[66:69], v42 offset:36736
	ds_read_b128 v[70:73], v42 offset:36752
	v_mul_f32_e32 v74, 0x3f317217, v78
	v_fma_f32 v85, v78, s36, -v74
	v_fmac_f32_e32 v85, 0x3377d1cf, v78
	s_waitcnt lgkmcnt(1)
	v_mov_b32_e32 v74, v66
	s_waitcnt lgkmcnt(0)
	v_mov_b32_e32 v75, v70
	v_mov_b32_e32 v70, v67
	v_pk_mul_f32 v[66:67], v[26:27], v[70:71]
	v_mov_b32_e32 v70, v68
	v_pk_fma_f32 v[66:67], v[24:25], v[74:75], v[66:67]
	v_mov_b32_e32 v71, v72
	v_pk_fma_f32 v[70:71], v[22:23], v[70:71], v[66:67]
	v_mov_b32_e32 v72, v69
	ds_read_b128 v[66:69], v42 offset:36768
	ds_read_b128 v[74:77], v42 offset:36784
	v_pk_fma_f32 v[70:71], v[28:29], v[72:73], v[70:71]
	v_fmac_f32_e32 v85, 0x3f317217, v78
	v_add_f32_e32 v70, v2, v70
	v_add_f32_e32 v72, v70, v71
	s_waitcnt lgkmcnt(0)
	v_mov_b32_e32 v71, v74
	v_mov_b32_e32 v74, v67
	v_mov_b32_e32 v70, v66
	v_pk_mul_f32 v[66:67], v[18:19], v[74:75]
	v_pk_fma_f32 v[66:67], v[14:15], v[70:71], v[66:67]
	v_mov_b32_e32 v70, v68
	v_mov_b32_e32 v71, v76
	v_pk_fma_f32 v[66:67], v[16:17], v[70:71], v[66:67]
	v_mov_b32_e32 v76, v69
	v_pk_fma_f32 v[66:67], v[20:21], v[76:77], v[66:67]
	v_add_f32_e32 v66, v72, v66
	v_add_f32_e32 v66, v66, v67
	v_mul_f32_e64 v67, |v66|, s4
	v_exp_f32_e32 v67, v67
	v_mov_b32_e32 v68, v85
	v_min_f32_e32 v78, 0, v66
	v_add_f32_e32 v67, 1.0, v67
	s_nop 1
	v_log_f32_e32 v76, v67
	v_mov_b32_e32 v67, v68
	v_sub_f32_e32 v77, v84, v67
	ds_read_b128 v[66:69], v42 offset:36800
	ds_read_b128 v[70:73], v42 offset:36816
	v_mul_f32_e32 v74, 0x3f317217, v76
	v_fma_f32 v84, v76, s36, -v74
	v_fmac_f32_e32 v84, 0x3377d1cf, v76
	s_waitcnt lgkmcnt(1)
	v_mov_b32_e32 v74, v66
	s_waitcnt lgkmcnt(0)
	v_mov_b32_e32 v75, v70
	v_mov_b32_e32 v70, v67
	v_pk_mul_f32 v[26:27], v[26:27], v[70:71]
	v_fmac_f32_e32 v84, 0x3f317217, v76
	v_pk_fma_f32 v[24:25], v[24:25], v[74:75], v[26:27]
	v_mov_b32_e32 v26, v68
	v_mov_b32_e32 v27, v72
	v_pk_fma_f32 v[26:27], v[22:23], v[26:27], v[24:25]
	v_mov_b32_e32 v72, v69
	ds_read_b128 v[22:25], v42 offset:36832
	ds_read_b128 v[66:69], v42 offset:36848
	v_pk_fma_f32 v[26:27], v[28:29], v[72:73], v[26:27]
	v_add_f32_e32 v2, v2, v26
	v_add_f32_e32 v2, v2, v27
	s_waitcnt lgkmcnt(0)
	v_mov_b32_e32 v27, v66
	v_mov_b32_e32 v66, v23
	v_mov_b32_e32 v26, v22
	v_pk_mul_f32 v[18:19], v[18:19], v[66:67]
	s_nop 0
	v_pk_fma_f32 v[14:15], v[14:15], v[26:27], v[18:19]
	v_mov_b32_e32 v18, v24
	v_mov_b32_e32 v19, v68
	v_pk_fma_f32 v[14:15], v[16:17], v[18:19], v[14:15]
	v_mov_b32_e32 v68, v25
	v_pk_fma_f32 v[14:15], v[20:21], v[68:69], v[14:15]
	v_add_f32_e32 v2, v2, v14
	v_add_f32_e32 v2, v2, v15
	v_mul_f32_e64 v14, |v2|, s4
	v_exp_f32_e32 v14, v14
	v_mov_b32_e32 v15, v84
	v_sub_f32_e32 v15, v78, v15
	v_add_f32_e32 v14, 1.0, v14
	v_min_f32_e32 v2, 0, v2
	s_nop 0
	v_fmamk_f32 v17, v49, 0x3d800000, v48
	v_fmamk_f32 v42, v50, 0x3d800000, v17
	v_fmamk_f32 v49, v51, 0x3d800000, v42
	v_fmamk_f32 v66, v52, 0x3d800000, v49
	v_fmamk_f32 v67, v53, 0x3d800000, v66
	v_fmamk_f32 v68, v54, 0x3d800000, v67
	v_fmamk_f32 v69, v55, 0x3d800000, v68
	v_fmamk_f32 v70, v56, 0x3d800000, v69
	v_fmamk_f32 v71, v57, 0x3d800000, v70
	v_fmamk_f32 v58, v58, 0x3d800000, v71
	v_fmamk_f32 v59, v59, 0x3d800000, v58
	v_fmamk_f32 v60, v60, 0x3d800000, v59
	v_fmamk_f32 v61, v61, 0x3d800000, v60
	v_log_f32_e32 v14, v14
	v_fmamk_f32 v62, v62, 0x3d800000, v61
	v_fmamk_f32 v63, v63, 0x3d800000, v62
	v_fmamk_f32 v64, v64, 0x3d800000, v63
	v_fmamk_f32 v65, v65, 0x3d800000, v64
	v_mul_f32_e32 v16, 0x3f317217, v14
	v_fmamk_f32 v72, v79, 0x3d800000, v65
	v_fma_f32 v16, v14, s36, -v16
	v_fmamk_f32 v73, v80, 0x3d800000, v72
	v_fmac_f32_e32 v16, 0x3377d1cf, v14
	v_fmamk_f32 v74, v81, 0x3d800000, v73
	v_fmac_f32_e32 v16, 0x3f317217, v14
	v_fmamk_f32 v75, v82, 0x3d800000, v74
	v_fmamk_f32 v76, v83, 0x3d800000, v75
	v_mov_b32_e32 v14, v16
	v_fmamk_f32 v77, v77, 0x3d800000, v76
	v_sub_f32_e32 v2, v2, v14
	v_fmamk_f32 v78, v15, 0x3d800000, v77
	v_lshl_add_u32 v14, s1, 2, v34
	v_fmamk_f32 v79, v2, 0x3d800000, v78
	ds_write_b32 v14, v79
	s_waitcnt lgkmcnt(0)
	s_barrier
; #define LAS __attribute__((address_space(3)))
; __device__ __forceinline__ float bf2f(bf16_t v) { return __uint_as_float((unsigned)v << 16); }
; #define X make_ctx(lds_raw)
; __device__ __forceinline__ void gla_bcum(KArgs a, int tid, int t0, int h, LAS float* segtot, LAS float* glrs, float (&bc)[32], float& tot) {
;     ...
;     float off = 0.f; tot = 0.f;
; #pragma unroll
;     for (int s2 = 0; s2 < 4; ++s2) { const float v = segtot[s2 * 128 + d]; tot += v; if (s2 < seg) off += v; }
; #pragma unroll
;     for (int r = 0; r < 32; ++r) bc[r] += off;
; }
; __device__ __forceinline__ void gla_stage_vT(const bf16_t* proj, int tid, int t0, int h, LAS bf16_t* vT) {
; #pragma unroll
;     for (int q = 0; q < 8; ++q) { const int i = tid >> 2, c = (tid & 3) + 4 * q;
;         const u32x4 wv = *(const u32x4*)(proj + (size_t)(t0 + i) * NMAIN + C_GV + h * 256 + 8 * c);
;         LAS bf16_t* vp = vT + (8 * c) * GP + i;
;         vp[0 * GP] = (bf16_t)(wv.x & 0xffff); vp[1 * GP] = (bf16_t)(wv.x >> 16); vp[2 * GP] = (bf16_t)(wv.y & 0xffff); vp[3 * GP] = (bf16_t)(wv.y >> 16);
;         vp[4 * GP] = (bf16_t)(wv.z & 0xffff); vp[5 * GP] = (bf16_t)(wv.z >> 16); vp[6 * GP] = (bf16_t)(wv.w & 0xffff); vp[7 * GP] = (bf16_t)(wv.w >> 16); }
; }
; __device__ __forceinline__ void gla_a1(const Ctx& X, KArgs a, float* kvt, float* decb) {
;     const bf16_t* proj = (const bf16_t*)(a->ws + WS_BIG);
;     LAS bf16_t* kdT = (LAS bf16_t*)X.lds; LAS bf16_t* vT = (LAS bf16_t*)(X.lds + 128 * GP * 2); LAS float* segtot = (LAS float*)(X.lds + 384 * GP * 2);
;     const int fr = X.lane & 15, fq = X.lane >> 4, w = X.wave;
;     for (int unit = blockIdx.x; unit < 512; unit += gridDim.x) {
;         const int bh = unit >> 5, n = unit & 31, b = bh >> 2, h = bh & 3, t0 = b * SEQ + n * 128;
;         __syncthreads();
;         float bc[32], tot; gla_bcum(a, X.tid, t0, h, segtot, (LAS float*)vT, bc, tot);
;         { const int d = X.tid & 127, seg = X.tid >> 7;
; #pragma unroll
;           for (int r8 = 0; r8 < 4; ++r8) { float kd[8];
; #pragma unroll
;               for (int e = 0; e < 8; ++e) { const int r = r8 * 8 + e; kd[e] = bf2f(proj[(size_t)(t0 + seg * 32 + r) * NMAIN + C_GK + h * 128 + d]) * __expf(tot - bc[r]); }
;               *(LAS u32x4*)(kdT + d * GP + seg * 32 + r8 * 8) = pack8(kd); }
	ds_read2st64_b32 v[14:15], v34 offset1:2
	ds_read2st64_b32 v[20:21], v34 offset0:4 offset1:6
	s_cselect_b64 s[6:7], -1, 0
	s_cmp_gt_i32 s0, 1
	s_waitcnt lgkmcnt(1)
	v_add_f32_e32 v2, 0, v14
	v_cndmask_b32_e64 v14, 0, v2, s[6:7]
	v_add_f32_e32 v16, v15, v14
	s_cselect_b64 s[6:7], -1, 0
	s_cmp_gt_i32 s0, 2
	v_cndmask_b32_e64 v14, v14, v16, s[6:7]
	s_waitcnt lgkmcnt(0)
	v_add_f32_e32 v18, v20, v14
	s_cselect_b64 s[6:7], -1, 0
	v_add_f32_e32 v2, v15, v2
	s_cmp_gt_i32 s0, 3
	v_add_f32_e32 v16, v20, v2
	v_cndmask_b32_e64 v2, v14, v18, s[6:7]
	v_add_f32_e32 v14, v21, v2
	s_cselect_b64 s[6:7], -1, 0
	v_cndmask_b32_e64 v19, v2, v14, s[6:7]
	s_nop 0
	s_nop 0
	s_nop 0
	v_mov_b32_e32 v18, v21
	v_add_f32_e32 v13, v13, v19
	v_pk_add_f32 v[16:17], v[18:19], v[16:17]
	v_add_f32_e32 v44, v44, v19
	v_add_f32_e32 v46, v46, v19
	v_sub_f32_e32 v13, v16, v13
	v_add_f32_e32 v25, v43, v19
	v_add_f32_e32 v26, v45, v19
	v_add_f32_e32 v27, v47, v19
	v_add_f32_e32 v28, v48, v19
	v_add_f32_e32 v21, v42, v19
	v_add_f32_e32 v42, v49, v19
	v_add_f32_e32 v43, v66, v19
	v_add_f32_e32 v55, v67, v19
	v_add_f32_e32 v56, v68, v19
	v_add_f32_e32 v57, v69, v19
	v_add_f32_e32 v66, v70, v19
	v_add_f32_e32 v67, v71, v19
	v_add_f32_e32 v58, v58, v19
	v_add_f32_e32 v59, v59, v19
	v_add_f32_e32 v60, v60, v19
	v_add_f32_e32 v61, v61, v19
	v_add_f32_e32 v62, v62, v19
	v_add_f32_e32 v63, v63, v19
	v_add_f32_e32 v64, v64, v19
	v_add_f32_e32 v65, v65, v19
	v_add_f32_e32 v68, v72, v19
	v_add_f32_e32 v69, v73, v19
	v_add_f32_e32 v70, v74, v19
	v_add_f32_e32 v71, v75, v19
	v_add_f32_e32 v72, v76, v19
	v_add_f32_e32 v73, v77, v19
	v_add_f32_e32 v74, v78, v19
	v_add_f32_e32 v75, v19, v79
	v_sub_f32_e32 v18, v16, v44
	v_sub_f32_e32 v19, v16, v46
	v_mul_f32_e32 v13, 0x3fb8aa3b, v13
	v_mul_f32_e32 v18, 0x3fb8aa3b, v18
	v_mul_f32_e32 v19, 0x3fb8aa3b, v19
	v_exp_f32_e32 v24, v13
	v_sub_f32_e32 v13, v16, v25
	v_exp_f32_e32 v18, v18
	v_exp_f32_e32 v19, v19
	v_mul_f32_e32 v13, 0x3fb8aa3b, v13
	v_exp_f32_e32 v25, v13
	s_waitcnt vmcnt(30)
	v_lshlrev_b32_e32 v23, 16, v193
	v_lshlrev_b32_e32 v22, 16, v192
	v_sub_f32_e32 v13, v16, v26
	v_pk_mul_f32 v[18:19], v[18:19], v[22:23]
	s_waitcnt vmcnt(28)
	v_lshlrev_b32_e32 v23, 16, v195
	v_lshlrev_b32_e32 v22, 16, v194
	v_mul_f32_e32 v13, 0x3fb8aa3b, v13
	v_pk_mul_f32 v[24:25], v[24:25], v[22:23]
	v_exp_f32_e32 v22, v13
	v_sub_f32_e32 v13, v16, v27
	v_mul_f32_e32 v13, 0x3fb8aa3b, v13
	v_exp_f32_e32 v23, v13
	v_sub_f32_e32 v13, v16, v28
	v_mul_f32_e32 v13, 0x3fb8aa3b, v13
	v_exp_f32_e32 v28, v13
	v_sub_f32_e32 v13, v16, v17
	v_mul_f32_e32 v13, 0x3fb8aa3b, v13
	v_exp_f32_e32 v29, v13
	s_waitcnt vmcnt(26)
	v_lshlrev_b32_e32 v27, 16, v197
	v_lshlrev_b32_e32 v26, 16, v196
	v_pk_mul_f32 v[26:27], v[22:23], v[26:27]
	s_waitcnt vmcnt(24)
	v_lshlrev_b32_e32 v23, 16, v199
	v_lshlrev_b32_e32 v22, 16, v198
	v_pk_mul_f32 v[28:29], v[28:29], v[22:23]
	v_cvt_pk_bf16_f32 v22, v18, v19
	v_cvt_pk_bf16_f32 v23, v24, v25
	v_cvt_pk_bf16_f32 v24, v26, v27
	v_cvt_pk_bf16_f32 v25, v28, v29
	v_sub_f32_e32 v13, v16, v21
	ds_write_b128 v37, v[22:25]
	v_mul_f32_e32 v13, 0x3fb8aa3b, v13
	v_exp_f32_e32 v18, v13
	v_sub_f32_e32 v13, v16, v42
	v_mul_f32_e32 v13, 0x3fb8aa3b, v13
	v_exp_f32_e32 v19, v13
	v_sub_f32_e32 v13, v16, v43
	s_waitcnt vmcnt(23)
	v_lshlrev_b32_e32 v22, 16, v200
	s_nop 0
	s_nop 0
	s_nop 0
	s_nop 0
	v_mul_f32_e32 v13, 0x3fb8aa3b, v13
	v_exp_f32_e32 v14, v13
	v_sub_f32_e32 v13, v16, v55
	v_mul_f32_e32 v13, 0x3fb8aa3b, v13
	v_exp_f32_e32 v15, v13
	v_sub_f32_e32 v13, v16, v56
	s_waitcnt vmcnt(20)
; #define LAS __attribute__((address_space(3)))
; __device__ __forceinline__ float bf2f(bf16_t v) { return __uint_as_float((unsigned)v << 16); }
; __device__ __forceinline__ u32x4 pack8(const float* f) { u32x4 w; w.x = pk2(f[0], f[1]); w.y = pk2(f[2], f[3]); w.z = pk2(f[4], f[5]); w.w = pk2(f[6], f[7]); return w; }
; __device__ __forceinline__ void gla_a1(const Ctx& X, KArgs a, float* kvt, float* decb) {
;     ...
;           for (int r8 = 0; r8 < 4; ++r8) { float kd[8];
; #pragma unroll
;               for (int e = 0; e < 8; ++e) { const int r = r8 * 8 + e; kd[e] = bf2f(proj[(size_t)(t0 + seg * 32 + r) * NMAIN + C_GK + h * 128 + d]) * __expf(tot - bc[r]); }
;               *(LAS u32x4*)(kdT + d * GP + seg * 32 + r8 * 8) = pack8(kd); }
;           if (seg == 0) decb[unit * 128 + d] = __expf(tot); }
	v_lshlrev_b32_e32 v21, 16, v203
	v_lshlrev_b32_e32 v20, 16, v202
	v_mul_f32_e32 v13, 0x3fb8aa3b, v13
	v_pk_mul_f32 v[14:15], v[14:15], v[20:21]
	v_exp_f32_e32 v20, v13
	v_sub_f32_e32 v13, v16, v57
	v_mul_f32_e32 v13, 0x3fb8aa3b, v13
	v_exp_f32_e32 v21, v13
	v_sub_f32_e32 v13, v16, v66
	v_mul_f32_e32 v13, 0x3fb8aa3b, v13
	v_exp_f32_e32 v24, v13
	v_sub_f32_e32 v13, v16, v67
	v_mul_f32_e32 v13, 0x3fb8aa3b, v13
	v_lshlrev_b32_e32 v23, 16, v201
	v_exp_f32_e32 v25, v13
	v_sub_f32_e32 v13, v16, v58
	v_pk_mul_f32 v[18:19], v[18:19], v[22:23]
	v_mul_f32_e32 v13, 0x3fb8aa3b, v13
	s_waitcnt vmcnt(18)
	v_lshlrev_b32_e32 v23, 16, v205
	v_lshlrev_b32_e32 v22, 16, v204
	v_cvt_pk_bf16_f32 v18, v18, v19
	v_cvt_pk_bf16_f32 v19, v14, v15
	v_exp_f32_e32 v14, v13
	v_sub_f32_e32 v13, v16, v59
	v_pk_mul_f32 v[20:21], v[20:21], v[22:23]
	s_waitcnt vmcnt(16)
	v_lshlrev_b32_e32 v23, 16, v207
	v_lshlrev_b32_e32 v22, 16, v206
	v_mul_f32_e32 v13, 0x3fb8aa3b, v13
	v_pk_mul_f32 v[22:23], v[24:25], v[22:23]
	v_exp_f32_e32 v15, v13
	v_sub_f32_e32 v13, v16, v60
	v_cvt_pk_bf16_f32 v20, v20, v21
	v_cvt_pk_bf16_f32 v21, v22, v23
	v_mul_f32_e32 v13, 0x3fb8aa3b, v13
	ds_write_b128 v37, v[18:21] offset:16
	v_exp_f32_e32 v20, v13
	v_sub_f32_e32 v13, v16, v61
	v_mul_f32_e32 v13, 0x3fb8aa3b, v13
	v_exp_f32_e32 v21, v13
	s_waitcnt vmcnt(14)
	v_lshlrev_b32_e32 v19, 16, v209
	v_lshlrev_b32_e32 v18, 16, v208
	v_sub_f32_e32 v13, v16, v62
	v_pk_mul_f32 v[14:15], v[14:15], v[18:19]
	s_waitcnt vmcnt(12)
	v_lshlrev_b32_e32 v19, 16, v211
	v_lshlrev_b32_e32 v18, 16, v210
	v_mul_f32_e32 v13, 0x3fb8aa3b, v13
	v_pk_mul_f32 v[20:21], v[20:21], v[18:19]
	v_exp_f32_e32 v18, v13
	v_sub_f32_e32 v13, v16, v63
	v_mul_f32_e32 v13, 0x3fb8aa3b, v13
	v_exp_f32_e32 v19, v13
	v_sub_f32_e32 v13, v16, v64
	v_mul_f32_e32 v13, 0x3fb8aa3b, v13
	v_exp_f32_e32 v24, v13
	v_sub_f32_e32 v13, v16, v65
	v_mul_f32_e32 v13, 0x3fb8aa3b, v13
	v_exp_f32_e32 v25, v13
	s_waitcnt vmcnt(10)
	v_lshlrev_b32_e32 v23, 16, v213
	v_lshlrev_b32_e32 v22, 16, v212
	v_pk_mul_f32 v[22:23], v[18:19], v[22:23]
	s_waitcnt vmcnt(8)
	v_lshlrev_b32_e32 v19, 16, v215
	v_lshlrev_b32_e32 v18, 16, v214
	v_pk_mul_f32 v[24:25], v[24:25], v[18:19]
	v_cvt_pk_bf16_f32 v18, v14, v15
	v_cvt_pk_bf16_f32 v19, v20, v21
	v_cvt_pk_bf16_f32 v20, v22, v23
	v_cvt_pk_bf16_f32 v21, v24, v25
	v_sub_f32_e32 v13, v16, v68
	ds_write_b128 v37, v[18:21] offset:32
	v_mul_f32_e32 v13, 0x3fb8aa3b, v13
	s_waitcnt vmcnt(6)
	v_lshlrev_b32_e32 v19, 16, v217
	v_sub_f32_e32 v2, v16, v70
	v_exp_f32_e32 v14, v13
	v_sub_f32_e32 v13, v16, v69
	v_mul_f32_e32 v2, 0x3fb8aa3b, v2
	v_mul_f32_e32 v13, 0x3fb8aa3b, v13
	v_exp_f32_e32 v20, v2
	v_sub_f32_e32 v2, v16, v71
	v_exp_f32_e32 v15, v13
	v_mul_f32_e32 v2, 0x3fb8aa3b, v2
	v_exp_f32_e32 v21, v2
	v_lshlrev_b32_e32 v18, 16, v216
	v_sub_f32_e32 v2, v16, v72
	v_pk_mul_f32 v[14:15], v[14:15], v[18:19]
	s_waitcnt vmcnt(4)
	v_lshlrev_b32_e32 v19, 16, v219
	v_lshlrev_b32_e32 v18, 16, v218
	v_mul_f32_e32 v2, 0x3fb8aa3b, v2
	v_pk_mul_f32 v[20:21], v[20:21], v[18:19]
	v_exp_f32_e32 v18, v2
	v_sub_f32_e32 v2, v16, v73
	v_mul_f32_e32 v2, 0x3fb8aa3b, v2
	v_exp_f32_e32 v19, v2
	v_sub_f32_e32 v2, v16, v74
	v_mul_f32_e32 v2, 0x3fb8aa3b, v2
	v_exp_f32_e32 v24, v2
	v_sub_f32_e32 v2, v16, v75
	v_mul_f32_e32 v2, 0x3fb8aa3b, v2
	v_exp_f32_e32 v25, v2
	s_waitcnt vmcnt(2)
	v_lshlrev_b32_e32 v23, 16, v221
	v_lshlrev_b32_e32 v22, 16, v220
	v_pk_mul_f32 v[22:23], v[18:19], v[22:23]
	s_waitcnt vmcnt(0)
	v_lshlrev_b32_e32 v19, 16, v223
	v_lshlrev_b32_e32 v18, 16, v222
	v_pk_mul_f32 v[24:25], v[24:25], v[18:19]
	v_cvt_pk_bf16_f32 v18, v14, v15
	v_cvt_pk_bf16_f32 v19, v20, v21
	v_cvt_pk_bf16_f32 v20, v22, v23
	v_cvt_pk_bf16_f32 v21, v24, v25
	ds_write_b128 v37, v[18:21] offset:48
	s_and_saveexec_b64 s[0:1], vcc
	s_cbranch_execz .LBB0_340
	v_mul_f32_e32 v2, 0x3fb8aa3b, v16
	v_exp_f32_e32 v2, v2
	v_add_u32_e32 v14, s3, v32
	v_ashrrev_i32_e32 v15, 31, v14
	v_lshl_add_u64 v[14:15], v[14:15], 2, s[16:17]
	global_store_dword v[14:15], v2, off
	s_branch .LBB0_340
